# strategy 9 loop-edge edits: K-loop counter/pointer updates moved in front of the iteration's last barrier (4 GEMMs); attention main-loop back edge rotated so the loop-back barrier is the loop head
# baseline (speedup 1.0000x reference)
; #define PG8_STAGE(bufoff, gbase, voff) do { _Pragma("unroll") for (int _i = 0; _i < 2; ++_i) \
;         __builtin_amdgcn_global_load_lds((const unsigned*)((const char*)(gbase) + (voff)[_i]), (PG8_LAS unsigned*)(lds + (bufoff) + ldsw + _i * 8192), 16, 0, 0); } while (0)
; #define PG8_LDA(dst, b, h) do { _Pragma("unroll") for (int m = 0; m < 4; ++m) _Pragma("unroll") for (int k = 0; k < 2; ++k) dst[m][k] = *(const PG8_LAS bf16x8*)(lds + PG8_SA(b, h) + aoff + m * 2048 + k * 1024); } while (0)
; #define PG8_LDB(dst, b, h) do { _Pragma("unroll") for (int n = 0; n < 2; ++n) _Pragma("unroll") for (int k = 0; k < 2; ++k) dst[n][k] = *(const PG8_LAS bf16x8*)(lds + PG8_SB(b, h) + boff + n * 2048 + k * 1024); } while (0)
; #define PG8_MMA(ai, bj, At, Bt) do { __builtin_amdgcn_s_setprio(1); _Pragma("unroll") for (int m = 0; m < 4; ++m) _Pragma("unroll") for (int n = 0; n < 2; ++n) _Pragma("unroll") for (int k = 0; k < 2; ++k) \
;         acc[ai][bj][m][n] = __builtin_amdgcn_mfma_f32_16x16x32_bf16(Bt[n][k], At[m][k], acc[ai][bj][m][n], 0, 0, 0); __builtin_amdgcn_s_setprio(0); } while (0)
; #define PG8_WAIT_V(n) asm volatile("s_waitcnt vmcnt(" #n ")" ::: "memory")
; #define PG8_WAIT_L(n) asm volatile("s_waitcnt lgkmcnt(" #n ")" ::: "memory")
; #define PG8_BAR __builtin_amdgcn_s_barrier()
; template <class Epi, class Sched, bool ALIGN_EPI = false, bool SP2 = false>
; __device__ __forceinline__ void gemm_phase(PG8_LAS unsigned char* lds, const Gemm g, const Sched& S, const Epi& E) {
;     ...
;             const char* a1 = cA + (size_t)(t + 1) * kstep;
;             const char* a2 = last ? nA : cA + (size_t)(t + 2) * kstep; const char* b2 = last ? nB : cB + (size_t)(t + 2) * kstep;
;             const char* a3 = a2 + kstep; const char* b3 = b2 + kstep;
;             if (last && has_next) S.a_ready(nxt);
;             if constexpr (SP2) {
;             PG8_LDB(B0, 0, 0); PG8_LDB(B1, 0, 1); PG8_SCHED; PG8_LDA(At, 0, 0); PG8_STAGE(PG8_SA(1, 1), a1 + hstep, voffA);
;             PG8_WAIT_V(8); PG8_WAIT_L(0); PG8_BAR; PG8_MMA(0, 0, At, B0); PG8_MMA(0, 1, At, B1); PG8_BAR; PG8_SCHED;
;             PG8_LDA(At, 0, 1); PG8_STAGE(PG8_SB(0, 0), b2, voffB); PG8_STAGE(PG8_SB(0, 1), b2 + hstep, voffB); PG8_STAGE(PG8_SA(0, 0), a2, voffA);
;             PG8_WAIT_V(8); PG8_WAIT_L(0); PG8_BAR; PG8_MMA(1, 0, At, B0); PG8_MMA(1, 1, At, B1); PG8_BAR; PG8_SCHED;
.LBB0_102:
	ds_read_b128 v[148:151], v156
	ds_read_b128 v[160:163], v156 offset:1024
	ds_read_b128 v[164:167], v156 offset:2048
	ds_read_b128 v[168:171], v156 offset:3072
	ds_read_b128 v[172:175], v157
	ds_read_b128 v[176:179], v157 offset:1024
	ds_read_b128 v[180:183], v157 offset:2048
	ds_read_b128 v[184:187], v157 offset:3072
	s_add_u32 s68, s66, 0xfffc0080
	s_addc_u32 s69, s67, -1
	s_cmp_eq_u32 s92, 12
	s_cselect_b32 s71, s5, s69
	s_cselect_b32 s70, s19, s68
	s_cselect_b32 s69, s17, s91
	s_cselect_b32 s68, s72, s73
	v_lshl_add_u64 v[152:153], s[66:67], 0, v[140:141]
	s_add_i32 m0, s65, 0xc000
	ds_read_b128 v[188:191], v158
	ds_read_b128 v[192:195], v158 offset:1024
	ds_read_b128 v[196:199], v158 offset:2048
	ds_read_b128 v[200:203], v158 offset:3072
	ds_read_b128 v[204:207], v158 offset:4096
	ds_read_b128 v[208:211], v158 offset:5120
	ds_read_b128 v[212:215], v158 offset:6144
	ds_read_b128 v[216:219], v158 offset:7168
	global_load_lds_dwordx4 v[152:153], off
	v_lshl_add_u64 v[152:153], s[66:67], 0, v[142:143]
	s_add_i32 m0, s65, 0xe000
	s_nop 0
	global_load_lds_dwordx4 v[152:153], off
	s_waitcnt vmcnt(8)
	s_waitcnt lgkmcnt(0)
	s_barrier
	s_waitcnt lgkmcnt(0)
	v_mfma_f32_16x16x32_bf16 v[126:129], v[148:151], v[188:191], v[126:129]
	v_mfma_f32_16x16x32_bf16 v[122:125], v[164:167], v[188:191], v[122:125]
	v_mfma_f32_16x16x32_bf16 v[110:113], v[148:151], v[196:199], v[110:113]
	v_mfma_f32_16x16x32_bf16 v[106:109], v[164:167], v[196:199], v[106:109]
	v_mfma_f32_16x16x32_bf16 v[94:97], v[148:151], v[204:207], v[94:97]
	v_mfma_f32_16x16x32_bf16 v[90:93], v[164:167], v[204:207], v[90:93]
	v_mfma_f32_16x16x32_bf16 v[78:81], v[148:151], v[212:215], v[78:81]
	v_mfma_f32_16x16x32_bf16 v[74:77], v[164:167], v[212:215], v[74:77]
	v_mfma_f32_16x16x32_bf16 v[126:129], v[160:163], v[192:195], v[126:129]
	v_mfma_f32_16x16x32_bf16 v[122:125], v[168:171], v[192:195], v[122:125]
	v_mfma_f32_16x16x32_bf16 v[110:113], v[160:163], v[200:203], v[110:113]
	v_mfma_f32_16x16x32_bf16 v[106:109], v[168:171], v[200:203], v[106:109]
	v_mfma_f32_16x16x32_bf16 v[94:97], v[160:163], v[208:211], v[94:97]
	v_mfma_f32_16x16x32_bf16 v[90:93], v[168:171], v[208:211], v[90:93]
	v_mfma_f32_16x16x32_bf16 v[78:81], v[160:163], v[216:219], v[78:81]
	v_mfma_f32_16x16x32_bf16 v[74:77], v[168:171], v[216:219], v[74:77]
	v_mfma_f32_16x16x32_bf16 v[118:121], v[172:175], v[188:191], v[118:121]
	v_mfma_f32_16x16x32_bf16 v[114:117], v[180:183], v[188:191], v[114:117]
	v_mfma_f32_16x16x32_bf16 v[102:105], v[172:175], v[196:199], v[102:105]
	v_mfma_f32_16x16x32_bf16 v[98:101], v[180:183], v[196:199], v[98:101]
	v_mfma_f32_16x16x32_bf16 v[86:89], v[172:175], v[204:207], v[86:89]
	v_mfma_f32_16x16x32_bf16 v[82:85], v[180:183], v[204:207], v[82:85]
	v_mfma_f32_16x16x32_bf16 v[70:73], v[172:175], v[212:215], v[70:73]
	v_mfma_f32_16x16x32_bf16 v[66:69], v[180:183], v[212:215], v[66:69]
	v_mfma_f32_16x16x32_bf16 v[118:121], v[176:179], v[192:195], v[118:121]
	v_mfma_f32_16x16x32_bf16 v[114:117], v[184:187], v[192:195], v[114:117]
	v_mfma_f32_16x16x32_bf16 v[102:105], v[176:179], v[200:203], v[102:105]
	v_mfma_f32_16x16x32_bf16 v[98:101], v[184:187], v[200:203], v[98:101]
	v_mfma_f32_16x16x32_bf16 v[86:89], v[176:179], v[208:211], v[86:89]
	v_mfma_f32_16x16x32_bf16 v[82:85], v[184:187], v[208:211], v[82:85]
	v_mfma_f32_16x16x32_bf16 v[70:73], v[176:179], v[216:219], v[70:73]
	v_mfma_f32_16x16x32_bf16 v[66:69], v[184:187], v[216:219], v[66:69]
	s_barrier
	s_add_i32 s93, s89, s76
	v_lshl_add_u64 v[152:153], s[68:69], 0, v[132:133]
	s_mov_b32 m0, s93
	ds_read_b128 v[188:191], v158 offset:16384
	ds_read_b128 v[192:195], v158 offset:17408
	ds_read_b128 v[196:199], v158 offset:18432
	ds_read_b128 v[200:203], v158 offset:19456
	ds_read_b128 v[204:207], v158 offset:20480
	ds_read_b128 v[208:211], v158 offset:21504
	ds_read_b128 v[212:215], v158 offset:22528
	ds_read_b128 v[216:219], v158 offset:23552
	global_load_lds_dwordx4 v[152:153], off
	s_add_i32 m0, s93, 0x2000
	s_add_u32 s94, s68, 0x40000
	v_lshl_add_u64 v[220:221], s[68:69], 0, v[136:137]
	s_addc_u32 s95, s69, 0
	s_add_i32 s93, s90, s76
	global_load_lds_dwordx4 v[220:221], off
	v_lshl_add_u64 v[222:223], s[94:95], 0, v[132:133]
	s_mov_b32 m0, s93
	v_lshl_add_u64 v[224:225], s[70:71], 0, v[134:135]
	global_load_lds_dwordx4 v[222:223], off
	v_lshl_add_u64 v[222:223], s[94:95], 0, v[136:137]
	s_add_i32 m0, s93, 0x2000
	s_nop 0
	global_load_lds_dwordx4 v[222:223], off
	v_lshl_add_u64 v[222:223], s[70:71], 0, v[130:131]
	s_mov_b32 m0, s65
	s_nop 0
	global_load_lds_dwordx4 v[222:223], off
	s_mov_b32 m0, s77
	s_nop 0
	global_load_lds_dwordx4 v[224:225], off
	s_waitcnt vmcnt(8)
	s_waitcnt lgkmcnt(0)
	s_barrier
; #define PG8_STAGE(bufoff, gbase, voff) do { _Pragma("unroll") for (int _i = 0; _i < 2; ++_i) \
;         __builtin_amdgcn_global_load_lds((const unsigned*)((const char*)(gbase) + (voff)[_i]), (PG8_LAS unsigned*)(lds + (bufoff) + ldsw + _i * 8192), 16, 0, 0); } while (0)
; #define PG8_LDA(dst, b, h) do { _Pragma("unroll") for (int m = 0; m < 4; ++m) _Pragma("unroll") for (int k = 0; k < 2; ++k) dst[m][k] = *(const PG8_LAS bf16x8*)(lds + PG8_SA(b, h) + aoff + m * 2048 + k * 1024); } while (0)
; #define PG8_LDB(dst, b, h) do { _Pragma("unroll") for (int n = 0; n < 2; ++n) _Pragma("unroll") for (int k = 0; k < 2; ++k) dst[n][k] = *(const PG8_LAS bf16x8*)(lds + PG8_SB(b, h) + boff + n * 2048 + k * 1024); } while (0)
; #define PG8_MMA(ai, bj, At, Bt) do { __builtin_amdgcn_s_setprio(1); _Pragma("unroll") for (int m = 0; m < 4; ++m) _Pragma("unroll") for (int n = 0; n < 2; ++n) _Pragma("unroll") for (int k = 0; k < 2; ++k) \
;         acc[ai][bj][m][n] = __builtin_amdgcn_mfma_f32_16x16x32_bf16(Bt[n][k], At[m][k], acc[ai][bj][m][n], 0, 0, 0); __builtin_amdgcn_s_setprio(0); } while (0)
; #define PG8_WAIT_V(n) asm volatile("s_waitcnt vmcnt(" #n ")" ::: "memory")
; #define PG8_WAIT_L(n) asm volatile("s_waitcnt lgkmcnt(" #n ")" ::: "memory")
; #define PG8_BAR __builtin_amdgcn_s_barrier()
; #define PG8_SCHED __builtin_amdgcn_sched_barrier(0)
; template <class Epi, class Sched, bool ALIGN_EPI = false, bool SP2 = false>
; __device__ __forceinline__ void gemm_phase(PG8_LAS unsigned char* lds, const Gemm g, const Sched& S, const Epi& E) {
;     ...
;             PG8_WAIT_V(8); PG8_WAIT_L(0); PG8_BAR; PG8_MMA(1, 0, At, B0); PG8_MMA(1, 1, At, B1); PG8_BAR; PG8_SCHED;
;             PG8_LDB(B0, 1, 0); PG8_LDB(B1, 1, 1); PG8_SCHED; PG8_LDA(At, 1, 0); PG8_STAGE(PG8_SA(0, 1), a2 + hstep, voffA);
;             PG8_WAIT_V(8); PG8_WAIT_L(0); PG8_BAR; PG8_MMA(0, 0, At, B0); PG8_MMA(0, 1, At, B1); PG8_BAR; PG8_SCHED;
	s_waitcnt lgkmcnt(0)
	v_mfma_f32_16x16x32_bf16 v[62:65], v[148:151], v[188:191], v[62:65]
	v_mfma_f32_16x16x32_bf16 v[58:61], v[164:167], v[188:191], v[58:61]
	v_mfma_f32_16x16x32_bf16 v[46:49], v[148:151], v[196:199], v[46:49]
	v_mfma_f32_16x16x32_bf16 v[42:45], v[164:167], v[196:199], v[42:45]
	v_mfma_f32_16x16x32_bf16 v[30:33], v[148:151], v[204:207], v[30:33]
	v_mfma_f32_16x16x32_bf16 v[26:29], v[164:167], v[204:207], v[26:29]
	v_mfma_f32_16x16x32_bf16 v[14:17], v[148:151], v[212:215], v[14:17]
	v_mfma_f32_16x16x32_bf16 v[10:13], v[164:167], v[212:215], v[10:13]
	v_mfma_f32_16x16x32_bf16 v[62:65], v[160:163], v[192:195], v[62:65]
	v_mfma_f32_16x16x32_bf16 v[58:61], v[168:171], v[192:195], v[58:61]
	v_mfma_f32_16x16x32_bf16 v[46:49], v[160:163], v[200:203], v[46:49]
	v_mfma_f32_16x16x32_bf16 v[42:45], v[168:171], v[200:203], v[42:45]
	v_mfma_f32_16x16x32_bf16 v[30:33], v[160:163], v[208:211], v[30:33]
	v_mfma_f32_16x16x32_bf16 v[26:29], v[168:171], v[208:211], v[26:29]
	v_mfma_f32_16x16x32_bf16 v[14:17], v[160:163], v[216:219], v[14:17]
	v_mfma_f32_16x16x32_bf16 v[10:13], v[168:171], v[216:219], v[10:13]
	v_mfma_f32_16x16x32_bf16 v[54:57], v[172:175], v[188:191], v[54:57]
	v_mfma_f32_16x16x32_bf16 v[50:53], v[180:183], v[188:191], v[50:53]
	v_mfma_f32_16x16x32_bf16 v[38:41], v[172:175], v[196:199], v[38:41]
	v_mfma_f32_16x16x32_bf16 v[34:37], v[180:183], v[196:199], v[34:37]
	v_mfma_f32_16x16x32_bf16 v[22:25], v[172:175], v[204:207], v[22:25]
	v_mfma_f32_16x16x32_bf16 v[18:21], v[180:183], v[204:207], v[18:21]
	v_mfma_f32_16x16x32_bf16 v[6:9], v[172:175], v[212:215], v[6:9]
	v_mfma_f32_16x16x32_bf16 v[2:5], v[180:183], v[212:215], v[2:5]
	v_mfma_f32_16x16x32_bf16 v[54:57], v[176:179], v[192:195], v[54:57]
	v_mfma_f32_16x16x32_bf16 v[50:53], v[184:187], v[192:195], v[50:53]
	v_mfma_f32_16x16x32_bf16 v[38:41], v[176:179], v[200:203], v[38:41]
	v_mfma_f32_16x16x32_bf16 v[34:37], v[184:187], v[200:203], v[34:37]
	v_mfma_f32_16x16x32_bf16 v[22:25], v[176:179], v[208:211], v[22:25]
	v_mfma_f32_16x16x32_bf16 v[18:21], v[184:187], v[208:211], v[18:21]
	v_mfma_f32_16x16x32_bf16 v[6:9], v[176:179], v[216:219], v[6:9]
	v_mfma_f32_16x16x32_bf16 v[2:5], v[184:187], v[216:219], v[2:5]
	s_barrier
	s_add_i32 s93, 0, 0x18000
	v_add_u32_e32 v138, s93, v154
	s_add_i32 s94, 0, 0x1c000
	ds_read_b128 v[148:151], v138
	ds_read_b128 v[160:163], v138 offset:1024
	ds_read_b128 v[164:167], v138 offset:2048
	ds_read_b128 v[168:171], v138 offset:3072
	v_add_u32_e32 v138, s94, v154
	ds_read_b128 v[172:175], v138
	ds_read_b128 v[176:179], v138 offset:1024
	ds_read_b128 v[180:183], v138 offset:2048
	ds_read_b128 v[184:187], v138 offset:3072
	s_add_u32 s70, s70, 0x40000
	s_addc_u32 s71, s71, 0
	s_mov_b32 m0, s78
	v_lshl_add_u64 v[226:227], s[70:71], 0, v[130:131]
	ds_read_b128 v[188:191], v158 offset:32768
	ds_read_b128 v[192:195], v158 offset:33792
	ds_read_b128 v[196:199], v158 offset:34816
	ds_read_b128 v[200:203], v158 offset:35840
	ds_read_b128 v[204:207], v158 offset:36864
	ds_read_b128 v[208:211], v158 offset:37888
	ds_read_b128 v[212:215], v158 offset:38912
	ds_read_b128 v[216:219], v158 offset:39936
	global_load_lds_dwordx4 v[226:227], off
	v_lshl_add_u64 v[226:227], s[70:71], 0, v[134:135]
	s_mov_b32 m0, s79
	s_nop 0
	global_load_lds_dwordx4 v[226:227], off
	s_waitcnt vmcnt(8)
	s_waitcnt lgkmcnt(0)
	s_barrier
	s_waitcnt lgkmcnt(0)
	v_mfma_f32_16x16x32_bf16 v[126:129], v[148:151], v[188:191], v[126:129]
	v_mfma_f32_16x16x32_bf16 v[122:125], v[164:167], v[188:191], v[122:125]
	v_mfma_f32_16x16x32_bf16 v[110:113], v[148:151], v[196:199], v[110:113]
	v_mfma_f32_16x16x32_bf16 v[106:109], v[164:167], v[196:199], v[106:109]
	v_mfma_f32_16x16x32_bf16 v[94:97], v[148:151], v[204:207], v[94:97]
	v_mfma_f32_16x16x32_bf16 v[90:93], v[164:167], v[204:207], v[90:93]
	v_mfma_f32_16x16x32_bf16 v[78:81], v[148:151], v[212:215], v[78:81]
	v_mfma_f32_16x16x32_bf16 v[74:77], v[164:167], v[212:215], v[74:77]
	v_mfma_f32_16x16x32_bf16 v[126:129], v[160:163], v[192:195], v[126:129]
	v_mfma_f32_16x16x32_bf16 v[122:125], v[168:171], v[192:195], v[122:125]
	v_mfma_f32_16x16x32_bf16 v[110:113], v[160:163], v[200:203], v[110:113]
	v_mfma_f32_16x16x32_bf16 v[106:109], v[168:171], v[200:203], v[106:109]
	v_mfma_f32_16x16x32_bf16 v[94:97], v[160:163], v[208:211], v[94:97]
	v_mfma_f32_16x16x32_bf16 v[90:93], v[168:171], v[208:211], v[90:93]
	v_mfma_f32_16x16x32_bf16 v[78:81], v[160:163], v[216:219], v[78:81]
	v_mfma_f32_16x16x32_bf16 v[74:77], v[168:171], v[216:219], v[74:77]
	v_mfma_f32_16x16x32_bf16 v[118:121], v[172:175], v[188:191], v[118:121]
	v_mfma_f32_16x16x32_bf16 v[114:117], v[180:183], v[188:191], v[114:117]
	v_mfma_f32_16x16x32_bf16 v[102:105], v[172:175], v[196:199], v[102:105]
	v_mfma_f32_16x16x32_bf16 v[98:101], v[180:183], v[196:199], v[98:101]
	v_mfma_f32_16x16x32_bf16 v[86:89], v[172:175], v[204:207], v[86:89]
	v_mfma_f32_16x16x32_bf16 v[82:85], v[180:183], v[204:207], v[82:85]
	v_mfma_f32_16x16x32_bf16 v[70:73], v[172:175], v[212:215], v[70:73]
	v_mfma_f32_16x16x32_bf16 v[66:69], v[180:183], v[212:215], v[66:69]
	v_mfma_f32_16x16x32_bf16 v[118:121], v[176:179], v[192:195], v[118:121]
	v_mfma_f32_16x16x32_bf16 v[114:117], v[184:187], v[192:195], v[114:117]
	v_mfma_f32_16x16x32_bf16 v[102:105], v[176:179], v[200:203], v[102:105]
	v_mfma_f32_16x16x32_bf16 v[98:101], v[184:187], v[200:203], v[98:101]
	v_mfma_f32_16x16x32_bf16 v[86:89], v[176:179], v[208:211], v[86:89]
	v_mfma_f32_16x16x32_bf16 v[82:85], v[184:187], v[208:211], v[82:85]
	v_mfma_f32_16x16x32_bf16 v[70:73], v[176:179], v[216:219], v[70:73]
	v_mfma_f32_16x16x32_bf16 v[66:69], v[184:187], v[216:219], v[66:69]
	s_barrier
; #define PG8_STAGE(bufoff, gbase, voff) do { _Pragma("unroll") for (int _i = 0; _i < 2; ++_i) \
;         __builtin_amdgcn_global_load_lds((const unsigned*)((const char*)(gbase) + (voff)[_i]), (PG8_LAS unsigned*)(lds + (bufoff) + ldsw + _i * 8192), 16, 0, 0); } while (0)
; #define PG8_LDA(dst, b, h) do { _Pragma("unroll") for (int m = 0; m < 4; ++m) _Pragma("unroll") for (int k = 0; k < 2; ++k) dst[m][k] = *(const PG8_LAS bf16x8*)(lds + PG8_SA(b, h) + aoff + m * 2048 + k * 1024); } while (0)
; #define PG8_MMA(ai, bj, At, Bt) do { __builtin_amdgcn_s_setprio(1); _Pragma("unroll") for (int m = 0; m < 4; ++m) _Pragma("unroll") for (int n = 0; n < 2; ++n) _Pragma("unroll") for (int k = 0; k < 2; ++k) \
;         acc[ai][bj][m][n] = __builtin_amdgcn_mfma_f32_16x16x32_bf16(Bt[n][k], At[m][k], acc[ai][bj][m][n], 0, 0, 0); __builtin_amdgcn_s_setprio(0); } while (0)
; #define PG8_WAIT_V(n) asm volatile("s_waitcnt vmcnt(" #n ")" ::: "memory")
; #define PG8_WAIT_L(n) asm volatile("s_waitcnt lgkmcnt(" #n ")" ::: "memory")
; #define PG8_BAR __builtin_amdgcn_s_barrier()
; #define PG8_SCHED __builtin_amdgcn_sched_barrier(0)
; template <class Epi, class Sched, bool ALIGN_EPI = false, bool SP2 = false>
; __device__ __forceinline__ void gemm_phase(PG8_LAS unsigned char* lds, const Gemm g, const Sched& S, const Epi& E) {
;     ...
;         for (int t = 0; t < nt; t += 2) {
;             if constexpr (Epi::HAS_MID) { if (t == Epi::MID_T) E.mid(acc, cur, wr, wc, fr, fq); }
;             const bool last = (t == nt - 2);
;     ...
;             PG8_LDA(At, 1, 1); PG8_STAGE(PG8_SB(1, 0), b3, voffB); PG8_STAGE(PG8_SB(1, 1), b3 + hstep, voffB); PG8_STAGE(PG8_SA(1, 0), a3, voffA);
;             PG8_WAIT_V(8); PG8_WAIT_L(0); PG8_BAR; PG8_MMA(1, 0, At, B0); PG8_MMA(1, 1, At, B1); PG8_BAR; PG8_SCHED;
	s_add_i32 s70, s93, s76
	v_lshl_add_u64 v[152:153], v[152:153], 0, s[10:11]
	s_mov_b32 m0, s70
	ds_read_b128 v[188:191], v158 offset:49152
	ds_read_b128 v[192:195], v158 offset:50176
	ds_read_b128 v[196:199], v158 offset:51200
	ds_read_b128 v[200:203], v158 offset:52224
	ds_read_b128 v[204:207], v158 offset:53248
	ds_read_b128 v[208:211], v158 offset:54272
	ds_read_b128 v[212:215], v158 offset:55296
	ds_read_b128 v[216:219], v158 offset:56320
	global_load_lds_dwordx4 v[152:153], off
	s_add_i32 m0, s70, 0x2000
	s_add_u32 s68, s68, 0x40080
	v_lshl_add_u64 v[152:153], v[220:221], 0, s[10:11]
	s_addc_u32 s69, s69, 0
	s_add_i32 s70, s94, s76
	global_load_lds_dwordx4 v[152:153], off
	v_lshl_add_u64 v[152:153], s[68:69], 0, v[132:133]
	s_mov_b32 m0, s70
	s_nop 0
	global_load_lds_dwordx4 v[152:153], off
	v_lshl_add_u64 v[152:153], s[68:69], 0, v[136:137]
	s_add_i32 m0, s70, 0x2000
	s_nop 0
	global_load_lds_dwordx4 v[152:153], off
	v_lshl_add_u64 v[152:153], v[222:223], 0, s[10:11]
	s_mov_b32 m0, s81
	s_nop 0
	global_load_lds_dwordx4 v[152:153], off
	v_lshl_add_u64 v[152:153], v[224:225], 0, s[10:11]
	s_mov_b32 m0, s82
	s_nop 0
	global_load_lds_dwordx4 v[152:153], off
	s_waitcnt vmcnt(8)
	s_waitcnt lgkmcnt(0)
	s_barrier
	s_waitcnt lgkmcnt(0)
	v_mfma_f32_16x16x32_bf16 v[62:65], v[148:151], v[188:191], v[62:65]
	v_mfma_f32_16x16x32_bf16 v[58:61], v[164:167], v[188:191], v[58:61]
	v_mfma_f32_16x16x32_bf16 v[46:49], v[148:151], v[196:199], v[46:49]
	v_mfma_f32_16x16x32_bf16 v[42:45], v[164:167], v[196:199], v[42:45]
	v_mfma_f32_16x16x32_bf16 v[30:33], v[148:151], v[204:207], v[30:33]
	v_mfma_f32_16x16x32_bf16 v[26:29], v[164:167], v[204:207], v[26:29]
	v_mfma_f32_16x16x32_bf16 v[14:17], v[148:151], v[212:215], v[14:17]
	v_mfma_f32_16x16x32_bf16 v[10:13], v[164:167], v[212:215], v[10:13]
	v_mfma_f32_16x16x32_bf16 v[62:65], v[160:163], v[192:195], v[62:65]
	v_mfma_f32_16x16x32_bf16 v[58:61], v[168:171], v[192:195], v[58:61]
	v_mfma_f32_16x16x32_bf16 v[46:49], v[160:163], v[200:203], v[46:49]
	v_mfma_f32_16x16x32_bf16 v[42:45], v[168:171], v[200:203], v[42:45]
	v_mfma_f32_16x16x32_bf16 v[30:33], v[160:163], v[208:211], v[30:33]
	v_mfma_f32_16x16x32_bf16 v[26:29], v[168:171], v[208:211], v[26:29]
	v_mfma_f32_16x16x32_bf16 v[14:17], v[160:163], v[216:219], v[14:17]
	v_mfma_f32_16x16x32_bf16 v[10:13], v[168:171], v[216:219], v[10:13]
	v_mfma_f32_16x16x32_bf16 v[54:57], v[172:175], v[188:191], v[54:57]
	v_mfma_f32_16x16x32_bf16 v[50:53], v[180:183], v[188:191], v[50:53]
	v_mfma_f32_16x16x32_bf16 v[38:41], v[172:175], v[196:199], v[38:41]
	v_mfma_f32_16x16x32_bf16 v[34:37], v[180:183], v[196:199], v[34:37]
	v_mfma_f32_16x16x32_bf16 v[22:25], v[172:175], v[204:207], v[22:25]
	v_mfma_f32_16x16x32_bf16 v[18:21], v[180:183], v[204:207], v[18:21]
	v_mfma_f32_16x16x32_bf16 v[6:9], v[172:175], v[212:215], v[6:9]
	v_mfma_f32_16x16x32_bf16 v[2:5], v[180:183], v[212:215], v[2:5]
	v_mfma_f32_16x16x32_bf16 v[54:57], v[176:179], v[192:195], v[54:57]
	v_mfma_f32_16x16x32_bf16 v[50:53], v[184:187], v[192:195], v[50:53]
	v_mfma_f32_16x16x32_bf16 v[38:41], v[176:179], v[200:203], v[38:41]
	v_mfma_f32_16x16x32_bf16 v[34:37], v[184:187], v[200:203], v[34:37]
	v_mfma_f32_16x16x32_bf16 v[22:25], v[176:179], v[208:211], v[22:25]
	v_mfma_f32_16x16x32_bf16 v[18:21], v[184:187], v[208:211], v[18:21]
	v_mfma_f32_16x16x32_bf16 v[6:9], v[176:179], v[216:219], v[6:9]
	v_mfma_f32_16x16x32_bf16 v[2:5], v[184:187], v[216:219], v[2:5]
	s_add_i32 s92, s92, 2
	s_add_u32 s66, s66, 0x100
	s_addc_u32 s67, s67, 0
	s_add_u32 s73, s73, 0x100
	s_addc_u32 s91, s91, 0
	s_cmp_gt_u32 s92, 13
	s_barrier
	s_cbranch_scc0 .LBB0_102
	s_and_b64 vcc, exec, s[12:13]
	s_cbranch_vccz .LBB0_105
	s_barrier

; #define SBAR() __builtin_amdgcn_sched_barrier(0)
; #define VMW() asm volatile("s_waitcnt vmcnt(0)" ::: "memory")
; #define SLOAD_H(Kp, Vp, k0) do { S.st_v0 = load8(ROWK(Vp, k0, sr)); S.st_v1 = load8(ROWK(Vp, k0, 32 + sr));              \
;                          S.st_k0 = load8(ROWK(Kp, k0, sr)); S.st_k1 = load8(ROWK(Kp, k0, 32 + sr)); } while (0)
; #define SWRITE_HV(bf) do { OPQ_TID(); const int vst0_ = v_st(sr_, sc_), vst1_ = v_st(32 + sr_, sc_); *(bf16x8*)(V_lds + (bf) * SHM_V + vst0_) = S.st_v0; *(bf16x8*)(V_lds + (bf) * SHM_V + vst1_) = S.st_v1; } while (0)
; #define SWRITE_H(bf) do { SWRITE_HV(bf); SWRITE_HK(bf); } while (0)
; #define MASKT(P0_, P1_, t) do { const int kb_ = KBASE(t); if (kb_ + KVBLK - 1 > qlo) mask_tile(P0_, P1_, qm - kb_, (unsigned)W); } while (0)
; __device__ __forceinline__ void partialSM(f32x16& p0, f32x16& p1, float& m_reg, float& mn, float& alpha) {
;     float pmax = p0[0]; for (int r = 1; r < 16; ++r) pmax = fmaxf(pmax, p0[r]); for (int r = 0; r < 16; ++r) pmax = fmaxf(pmax, p1[r]);
;     { auto rr = __builtin_amdgcn_permlane32_swap(__float_as_uint(pmax), __float_as_uint(pmax), false, false);
;       pmax = fmaxf(__uint_as_float(rr[0]), __uint_as_float(rr[1])); }
;     constexpr float C2 = 1.4426950408889634f * SCALE;
;     if (__builtin_expect(__all((pmax - m_reg) * SCALE <= THR), 1)) { mn = m_reg; alpha = 1.f; }
;     else { mn = fmaxf(m_reg, pmax); alpha = __builtin_amdgcn_exp2f((m_reg - mn) * C2); m_reg = mn; }
;     const float mnL = -mn * C2;
;     for (int r = 0; r < 16; ++r) p0[r] = fmaf(p0[r], C2, mnL); for (int r = 0; r < 16; ++r) p1[r] = fmaf(p1[r], C2, mnL);
;     for (int r = 0; r < 16; ++r) p0[r] = __builtin_amdgcn_exp2f(p0[r]);
; __device__ __forceinline__ void fox_block(const BlockRef& cur, const BlockRef& nxt, char* lds, char* cbcur, char* cbnxt, Seam& S) {
;     ...
;     SWRITE_HV(0); SBAR();
;     if (NT > 1) { SLOAD_H(Kh, Vh, KBASE(1)); }
;     SBAR(); qkt<0>(pA0, pA1, K_lds, cbl + 8 * KBASE(0), r32, hi, S.qr);
;     MASKT(pA0, pA1, 0); partialSM(pA0, pA1, m_reg, mnA, alA);
;     if (NT > 1) { VMW(); SWRITE_H(1); }
;     __syncthreads();
.LBB0_229:
	s_nop 8
	v_max_f32_e32 v50, v19, v19
	v_max_f32_e32 v51, v18, v18
	v_max_f32_e32 v50, v51, v50
	v_max3_f32 v50, v50, v20, v21
	v_max3_f32 v50, v50, v22, v23
	v_max3_f32 v50, v50, v24, v25
	v_max3_f32 v50, v50, v26, v27
	v_max3_f32 v50, v50, v28, v29
	v_max3_f32 v50, v50, v30, v31
	v_max3_f32 v50, v50, v32, v33
	v_max3_f32 v50, v50, v2, v3
	v_max3_f32 v50, v50, v4, v5
	v_max3_f32 v50, v50, v6, v7
	v_max3_f32 v50, v50, v8, v9
	v_max3_f32 v50, v50, v10, v11
	v_max3_f32 v50, v50, v12, v13
	v_max3_f32 v50, v50, v14, v15
	v_max3_f32 v50, v50, v16, v17
	v_mov_b32_e32 v51, v50
	s_nop 1
	v_permlane32_swap_b32_e32 v50, v51
	v_max_f32_e32 v51, v51, v51
	v_max_f32_e32 v50, v50, v50
	v_max_f32_e32 v50, v50, v51
	s_and_b32 s89, s85, 0x3fffffc0
	v_add_f32_e32 v51, 0x7149f2ca, v50
	s_lshl_b32 s89, s89, 2
	v_mul_f32_e32 v51, 0x3db504f3, v51
	v_max_f32_e32 v50, 0xf149f2ca, v50
	s_add_i32 s89, s89, 0
	v_cmp_ge_f32_e32 vcc, s78, v51
	v_sub_f32_e32 v51, 0xf149f2ca, v50
	s_add_i32 s89, s89, 0x10000
	v_mul_f32_e32 v51, 0x3e0293ee, v51
	v_exp_f32_e32 v51, v51
	s_cmp_eq_u64 vcc, exec
	s_cselect_b64 vcc, -1, 0
	v_cndmask_b32_e32 v217, v50, v210, vcc
	v_mul_f32_e32 v50, 0xbe0293ee, v217
	v_cndmask_b32_e64 v187, v51, 1.0, vcc
	v_mov_b32_e32 v51, v50
	v_fmac_f32_e32 v51, 0x3e0293ee, v33
	v_pk_fma_f32 v[126:127], v[2:3], s[16:17], v[50:51] op_sel_hi:[1,0,0]
	v_mov_b32_e32 v2, v0
	s_waitcnt vmcnt(0)
	v_pk_fma_f32 v[124:125], v[4:5], s[16:17], v[50:51] op_sel_hi:[1,0,0]
	v_ashrrev_i32_e32 v3, 4, v2
	v_and_b32_e32 v4, 0xfffff0, v3
	v_lshlrev_b32_e32 v5, 1, v3
	v_pk_fma_f32 v[120:121], v[6:7], s[16:17], v[50:51] op_sel_hi:[1,0,0]
	v_and_or_b32 v4, v5, 8, v4
	v_lshrrev_b32_e32 v5, 1, v3
	v_and_b32_e32 v7, 3, v3
	v_add_u32_e32 v3, 32, v3
	v_and_or_b32 v5, v5, 4, v7
	v_and_b32_e32 v7, 0xfffff0, v3
	v_lshlrev_b32_e32 v3, 1, v3
	v_and_or_b32 v3, v3, 8, v7
	v_lshrrev_b32_e32 v4, 1, v4
	v_bfe_u32 v6, v2, 2, 2
	v_lshrrev_b32_e32 v3, 1, v3
	v_or_b32_e32 v4, v4, v6
	v_lshlrev_b32_e32 v2, 4, v2
	v_or_b32_e32 v3, v3, v6
	v_lshlrev_b32_e32 v4, 9, v4
	v_and_b32_e32 v2, 48, v2
	v_lshlrev_b32_e32 v3, 9, v3
	v_lshl_add_u32 v5, v5, 6, 0
	v_add3_u32 v4, v5, v4, v2
	v_add3_u32 v2, v5, v3, v2
	s_waitcnt vmcnt(3)
	ds_write_b128 v4, v[46:49] offset:16384
	s_waitcnt vmcnt(2)
	ds_write_b128 v2, v[42:45] offset:16384
	v_mov_b32_e32 v2, v0
	v_fmamk_f32 v18, v18, 0x3e0293ee, v50
	v_lshlrev_b32_e32 v3, 4, v2
	v_and_b32_e32 v2, 0x70, v2
	v_and_b32_e32 v4, 0xffffff00, v3
	v_bitop3_b32 v2, v3, v2, s79 bitop3:0x6c
	v_fmamk_f32 v19, v19, 0x3e0293ee, v50
	v_fmamk_f32 v20, v20, 0x3e0293ee, v50
	v_fmamk_f32 v21, v21, 0x3e0293ee, v50
	v_fmamk_f32 v22, v22, 0x3e0293ee, v50
	v_fmamk_f32 v23, v23, 0x3e0293ee, v50
	v_fmamk_f32 v24, v24, 0x3e0293ee, v50
	v_fmamk_f32 v25, v25, 0x3e0293ee, v50
	v_fmamk_f32 v26, v26, 0x3e0293ee, v50
	v_fmamk_f32 v27, v27, 0x3e0293ee, v50
	v_fmamk_f32 v28, v28, 0x3e0293ee, v50
	v_fmamk_f32 v29, v29, 0x3e0293ee, v50
	v_fmamk_f32 v30, v30, 0x3e0293ee, v50
	v_fmamk_f32 v31, v31, 0x3e0293ee, v50
	v_fmamk_f32 v32, v32, 0x3e0293ee, v50
	v_add3_u32 v2, 0, v4, v2
	v_exp_f32_e32 v234, v18
	v_exp_f32_e32 v236, v19
	v_exp_f32_e32 v232, v20
	v_exp_f32_e32 v235, v21
	v_exp_f32_e32 v231, v22
	v_exp_f32_e32 v233, v23
	v_exp_f32_e32 v229, v24
	v_exp_f32_e32 v230, v25
	v_exp_f32_e32 v226, v26
	v_exp_f32_e32 v228, v27
	v_exp_f32_e32 v225, v28
	v_exp_f32_e32 v227, v29
	v_exp_f32_e32 v222, v30
	v_exp_f32_e32 v224, v31
	v_exp_f32_e32 v221, v32
	v_exp_f32_e32 v223, v51
	s_waitcnt vmcnt(1)
	ds_write_b128 v2, v[34:37] offset:49152
	s_waitcnt vmcnt(0)
	ds_write_b128 v2, v[38:41] offset:57344
	v_add_u32_e32 v2, 0xc0, v198
	v_pk_fma_f32 v[118:119], v[16:17], s[16:17], v[50:51] op_sel_hi:[1,0,0]
	v_lshl_add_u64 v[190:191], s[4:5], 0, v[182:183]
	v_add_u32_e32 v2, s76, v2
	s_lshl_b32 s4, s77, 6
	v_mov_b32_e32 v16, v183
	v_mov_b32_e32 v17, v183
	v_pk_fma_f32 v[122:123], v[14:15], s[16:17], v[50:51] op_sel_hi:[1,0,0]
	v_pk_fma_f32 v[128:129], v[12:13], s[16:17], v[50:51] op_sel_hi:[1,0,0]
	v_pk_fma_f32 v[114:115], v[10:11], s[16:17], v[50:51] op_sel_hi:[1,0,0]
	v_pk_fma_f32 v[116:117], v[8:9], s[16:17], v[50:51] op_sel_hi:[1,0,0]
	v_subrev_u32_e32 v216, s4, v2
	v_mov_b32_e32 v2, v183
	v_mov_b32_e32 v3, v183
	v_mov_b32_e32 v4, v183
	v_mov_b32_e32 v5, v183
	v_mov_b32_e32 v6, v183
	v_mov_b32_e32 v7, v183
	v_mov_b32_e32 v8, v183
	v_mov_b32_e32 v9, v183
	v_mov_b32_e32 v10, v183
	v_mov_b32_e32 v11, v183
	v_mov_b32_e32 v12, v183
	v_mov_b32_e32 v13, v183
	v_mov_b32_e32 v14, v183
	v_mov_b32_e32 v15, v183
	v_mov_b64_e32 v[64:65], v[16:17]
	v_mov_b64_e32 v[48:49], v[16:17]
	v_mov_b64_e32 v[32:33], v[16:17]
	s_mov_b32 s85, 2
	v_lshl_add_u64 v[188:189], s[74:75], 0, v[182:183]
	v_lshl_add_u32 v212, v1, 2, s89
	v_lshl_add_u32 v211, v203, 2, s89
	v_lshl_add_u32 v215, s77, 9, v202
	s_add_i32 s89, s4, 0xffffffbf
	v_mov_b32_e32 v214, 0
	v_mov_b64_e32 v[62:63], v[14:15]
	v_mov_b64_e32 v[60:61], v[12:13]
	v_mov_b64_e32 v[58:59], v[10:11]
	v_mov_b64_e32 v[56:57], v[8:9]
	v_mov_b64_e32 v[54:55], v[6:7]
	v_mov_b64_e32 v[52:53], v[4:5]
	v_mov_b64_e32 v[50:51], v[2:3]
	v_mov_b64_e32 v[46:47], v[14:15]
	v_mov_b64_e32 v[44:45], v[12:13]
	v_mov_b64_e32 v[42:43], v[10:11]
	v_mov_b64_e32 v[40:41], v[8:9]
	v_mov_b64_e32 v[38:39], v[6:7]
	v_mov_b64_e32 v[36:37], v[4:5]
	v_mov_b64_e32 v[34:35], v[2:3]
	v_mov_b64_e32 v[30:31], v[14:15]
	v_mov_b64_e32 v[28:29], v[12:13]
	v_mov_b64_e32 v[26:27], v[10:11]
	v_mov_b64_e32 v[24:25], v[8:9]
	v_mov_b64_e32 v[22:23], v[6:7]
	v_mov_b64_e32 v[20:21], v[4:5]
	v_mov_b64_e32 v[18:19], v[2:3]
	v_and_b32_e32 v239, 0x70, v0
	v_and_b32_e32 v201, 0xffffff00, v184
	v_and_b32_e32 v1, 0xf0, v184
	v_xor_b32_e32 v1, v1, v239
	v_add_u32_e32 v201, v201, v1
	v_bfe_u32 v1, v0, 6, 1
	v_lshlrev_b32_e32 v1, 11, v1
	v_bfe_u32 v239, v0, 8, 1
	v_lshl_or_b32 v1, v239, 12, v1
	v_bfe_u32 v239, v0, 2, 2
	v_lshl_or_b32 v1, v239, 9, v1
	v_bfe_u32 v239, v0, 4, 2
	v_lshl_or_b32 v1, v239, 6, v1
	v_bfe_u32 v239, v0, 7, 1
	v_lshl_or_b32 v1, v239, 8, v1
	v_and_b32_e32 v239, 3, v0
	v_lshl_or_b32 v1, v239, 4, v1
	v_lshlrev_b32_e32 v239, 2, v0
	s_waitcnt lgkmcnt(0)
; template <int KB>
; __device__ __forceinline__ void qkt(f32x16& p0, f32x16& p1, const char* K_lds, const char* cbt, int r32, int hi, const bf16x8* qr) {
;     { const u32x2 e0 = *(const u32x2*)(cbt), e1 = *(const u32x2*)(cbt + 32 * 8);
;       const unsigned c0 = hi ? 0u : 0x3F803F80u, c1 = hi ? 0u : 0x00003F80u;
;       const u32x4 k0 = {e0.x, e0.y, e0.x, e0.y}, k1 = {e1.x, e1.y, e1.x, e1.y}, q1 = {c0, c1, 0u, 0u};
;       p0 = __builtin_amdgcn_mfma_f32_32x32x16_bf16(__builtin_bit_cast(bf16x8, k0), __builtin_bit_cast(bf16x8, q1), f32x16{}, 0, 0, 0);
;       p1 = __builtin_amdgcn_mfma_f32_32x32x16_bf16(__builtin_bit_cast(bf16x8, k1), __builtin_bit_cast(bf16x8, q1), f32x16{}, 0, 0, 0); }
;     const char* kb[4];
; #pragma unroll
;     for (int dd = 0; dd < 4; ++dd) kb[dd] = K_lds + KB * SHM_K + KSWZ(r32, (dd * 16 + hi * 8) * 2);
; #pragma unroll
;     for (int d0 = 0; d0 < 8; ++d0) { const char* a = kb[d0 & 3] + (d0 >> 2) * 128;
;         bf16x8 b0 = *reinterpret_cast<const bf16x8*>(a);
;         bf16x8 b1 = *reinterpret_cast<const bf16x8*>(a + 32 * 256);
;         p0 = __builtin_amdgcn_mfma_f32_32x32x16_bf16(b0, qr[d0], p0, 0, 0, 0);
;         p1 = __builtin_amdgcn_mfma_f32_32x32x16_bf16(b1, qr[d0], p1, 0, 0, 0); }
; }
.Lattn_loop_head:
	s_barrier
.LBB0_230:
	v_add_u32_e32 v102, s89, v192
	v_add_u32_e32 v66, 0xffffff81, v102
	v_ashrrev_i32_e32 v67, 31, v66
	v_add_u32_e32 v70, 0xffffffa1, v102
	v_lshlrev_b64 v[66:67], 11, v[66:67]
	v_ashrrev_i32_e32 v71, 31, v70
	v_lshl_add_u64 v[68:69], v[188:189], 0, v[66:67]
	v_lshlrev_b64 v[70:71], 11, v[70:71]
	v_lshl_add_u64 v[66:67], v[190:191], 0, v[66:67]
	v_lshl_add_u64 v[72:73], v[188:189], 0, v[70:71]
	global_load_dwordx4 v[174:177], v[68:69], off
	global_load_dwordx4 v[170:173], v[72:73], off
	v_lshl_add_u64 v[68:69], v[190:191], 0, v[70:71]
	global_load_dwordx4 v[166:169], v[66:67], off
	global_load_dwordx4 v[178:181], v[68:69], off
	ds_read2_b64 v[66:69], v215 offset0:64 offset1:96
	v_exp_f32_e32 v103, v126
	v_exp_f32_e32 v108, v127
	v_exp_f32_e32 v109, v124
	v_exp_f32_e32 v110, v125
	s_waitcnt lgkmcnt(0)
	v_mov_b32_e32 v70, v66
	v_mov_b32_e32 v71, v67
	v_mov_b32_e32 v72, v66
	v_mov_b32_e32 v73, v67
	v_mov_b32_e32 v66, v68
	v_mov_b32_e32 v67, v69
	v_mfma_f32_32x32x16_bf16 v[86:101], v[70:73], v[162:165], 0
	v_exp_f32_e32 v111, v120
	v_exp_f32_e32 v112, v121
	v_exp_f32_e32 v113, v116
	v_exp_f32_e32 v116, v117
	v_exp_f32_e32 v114, v114
	v_exp_f32_e32 v115, v115
	v_exp_f32_e32 v117, v128
	v_mfma_f32_32x32x16_bf16 v[70:85], v[66:69], v[162:165], 0
	ds_read_b128 v[66:69], v205 offset:49152
	ds_read_b128 v[104:107], v205 offset:57344
	v_exp_f32_e32 v120, v129
	v_exp_f32_e32 v121, v122
	v_exp_f32_e32 v122, v123
	v_exp_f32_e32 v118, v118
	v_exp_f32_e32 v119, v119
	s_waitcnt lgkmcnt(1)
	v_mfma_f32_32x32x16_bf16 v[86:101], v[66:69], v[158:161], v[86:101]
	s_waitcnt lgkmcnt(0)
	v_mfma_f32_32x32x16_bf16 v[70:85], v[104:107], v[158:161], v[70:85]
	ds_read_b128 v[66:69], v206 offset:49152
	ds_read_b128 v[104:107], v206 offset:57344
	s_waitcnt lgkmcnt(1)
	v_mfma_f32_32x32x16_bf16 v[86:101], v[66:69], v[154:157], v[86:101]
	s_waitcnt lgkmcnt(0)
	v_mfma_f32_32x32x16_bf16 v[70:85], v[104:107], v[154:157], v[70:85]
	ds_read_b128 v[66:69], v207 offset:49152
	ds_read_b128 v[104:107], v207 offset:57344
	s_waitcnt lgkmcnt(1)
	v_mfma_f32_32x32x16_bf16 v[86:101], v[66:69], v[150:153], v[86:101]
	s_waitcnt lgkmcnt(0)
	v_mfma_f32_32x32x16_bf16 v[70:85], v[104:107], v[150:153], v[70:85]
	ds_read_b128 v[66:69], v208 offset:49152
	ds_read_b128 v[104:107], v208 offset:57344
	s_waitcnt lgkmcnt(1)
	v_mfma_f32_32x32x16_bf16 v[86:101], v[66:69], v[146:149], v[86:101]
	s_waitcnt lgkmcnt(0)
	v_mfma_f32_32x32x16_bf16 v[70:85], v[104:107], v[146:149], v[70:85]
	ds_read_b128 v[66:69], v205 offset:49280
	ds_read_b128 v[104:107], v205 offset:57472
	s_waitcnt lgkmcnt(1)
	v_mfma_f32_32x32x16_bf16 v[86:101], v[66:69], v[142:145], v[86:101]
	s_waitcnt lgkmcnt(0)
	v_mfma_f32_32x32x16_bf16 v[70:85], v[104:107], v[142:145], v[70:85]
	ds_read_b128 v[66:69], v206 offset:49280
	ds_read_b128 v[104:107], v206 offset:57472
	s_waitcnt lgkmcnt(1)
	v_mfma_f32_32x32x16_bf16 v[86:101], v[66:69], v[138:141], v[86:101]
	s_waitcnt lgkmcnt(0)
	v_mfma_f32_32x32x16_bf16 v[70:85], v[104:107], v[138:141], v[70:85]
	ds_read_b128 v[66:69], v207 offset:49280
	ds_read_b128 v[104:107], v207 offset:57472
	s_waitcnt lgkmcnt(1)
	v_mfma_f32_32x32x16_bf16 v[86:101], v[66:69], v[134:137], v[86:101]
	s_waitcnt lgkmcnt(0)
	v_mfma_f32_32x32x16_bf16 v[70:85], v[104:107], v[134:137], v[70:85]
	ds_read_b128 v[66:69], v208 offset:49280
	ds_read_b128 v[104:107], v208 offset:57472
	s_waitcnt lgkmcnt(1)
	v_mfma_f32_32x32x16_bf16 v[86:101], v[66:69], v[130:133], v[86:101]
	v_add_f32_e32 v66, 0, v234
	v_add_f32_e32 v66, v236, v66
	v_add_f32_e32 v66, v232, v66
	v_add_f32_e32 v66, v235, v66
	v_add_f32_e32 v66, v231, v66
	v_add_f32_e32 v66, v233, v66
	v_add_f32_e32 v66, v229, v66
	v_add_f32_e32 v66, v230, v66
	v_add_f32_e32 v66, v226, v66
	v_add_f32_e32 v66, v228, v66
	v_add_f32_e32 v66, v225, v66
	v_add_f32_e32 v66, v227, v66
	v_add_f32_e32 v66, v222, v66
	v_add_f32_e32 v66, v224, v66
	v_add_f32_e32 v66, v221, v66
	v_add_f32_e32 v66, v223, v66
	v_add_f32_e32 v66, v103, v66
	v_add_f32_e32 v66, v108, v66
	v_add_f32_e32 v66, v109, v66
	v_add_f32_e32 v66, v110, v66
	v_add_f32_e32 v66, v111, v66
	v_add_f32_e32 v66, v112, v66
	v_add_f32_e32 v66, v113, v66
	v_add_f32_e32 v66, v116, v66
	v_add_f32_e32 v66, v114, v66
	v_add_f32_e32 v66, v115, v66
	s_waitcnt lgkmcnt(0)
	v_mfma_f32_32x32x16_bf16 v[70:85], v[104:107], v[130:133], v[70:85]
	v_add_f32_e32 v66, v117, v66
	v_add_f32_e32 v66, v120, v66
	v_add_f32_e32 v66, v121, v66
	v_add_f32_e32 v66, v122, v66
	v_add_f32_e32 v66, v118, v66
	v_add_f32_e32 v218, v119, v66
	v_mov_b32_e32 v219, v218
	s_nop 1
	v_permlane32_swap_b32_e32 v218, v219
	v_cvt_pk_bf16_f32 v66, v234, v236
	v_cvt_pk_bf16_f32 v67, v232, v235
	v_cvt_pk_bf16_f32 v68, v231, v233
	v_cvt_pk_bf16_f32 v69, v229, v230
	v_cvt_pk_bf16_f32 v104, v226, v228
	v_cvt_pk_bf16_f32 v105, v225, v227
	v_cvt_pk_bf16_f32 v106, v222, v224
	v_cvt_pk_bf16_f32 v107, v221, v223
	v_cvt_pk_bf16_f32 v108, v103, v108
	v_cvt_pk_bf16_f32 v109, v109, v110
	v_cvt_pk_bf16_f32 v110, v111, v112
	v_cvt_pk_bf16_f32 v111, v113, v116
	v_cvt_pk_bf16_f32 v112, v114, v115
	v_cvt_pk_bf16_f32 v113, v117, v120
	v_cvt_pk_bf16_f32 v114, v121, v122
	v_cvt_pk_bf16_f32 v115, v118, v119
	s_nop 0
	v_permlane32_swap_b32_e32 v66, v68
	v_permlane32_swap_b32_e32 v67, v69
	v_permlane32_swap_b32_e32 v104, v106
	v_permlane32_swap_b32_e32 v105, v107
	v_permlane32_swap_b32_e32 v108, v110
	v_permlane32_swap_b32_e32 v109, v111
	v_permlane32_swap_b32_e32 v112, v114
	v_permlane32_swap_b32_e32 v113, v115
	ds_read_b64_tr_b16 v[116:117], v199 offset:0
	ds_read_b64_tr_b16 v[118:119], v199 offset:0x800
	ds_read_b64_tr_b16 v[120:121], v199 offset:0x200
	ds_read_b64_tr_b16 v[122:123], v199 offset:0xa00
	ds_read_b64_tr_b16 v[124:125], v199 offset:0x1000
	ds_read_b64_tr_b16 v[126:127], v199 offset:0x1800
	ds_read_b64_tr_b16 v[220:221], v199 offset:0x1200
	ds_read_b64_tr_b16 v[222:223], v199 offset:0x1a00
	s_waitcnt lgkmcnt(0)
; __device__ __forceinline__ void mask_tile(f32x16& p0, f32x16& p1, int dq, unsigned W) {
;     const float NEG = -__builtin_inff();
; #pragma unroll
;     for (int r = 0; r < 16; ++r) {
;         const int c = (r & 3) + 8 * (r >> 2);
;         if ((unsigned)(dq - c) >= W) p0[r] = NEG;
;         if ((unsigned)(dq - c - 32) >= W) p1[r] = NEG;
;     }
; }
; template <int VB>
; __device__ __forceinline__ void pv_tile(f32x16* o, int vb0, bf16x8 pa0, bf16x8 pa1, bf16x8 pa2, bf16x8 pa3) {
;     ...
;     PV_R(0, 0, pa0, pa1); PV_R(0, 2, pa2, pa3); PV_R(2, 0, pa0, pa1); PV_R(2, 2, pa2, pa3);
	s_nop 0
	v_mfma_f32_32x32x16_bf16 v[2:17], v[66:69], v[116:119], v[2:17]
	ds_read_b64_tr_b16 v[116:117], v199 offset:0x2000
	ds_read_b64_tr_b16 v[118:119], v199 offset:0x2800
	v_mfma_f32_32x32x16_bf16 v[50:65], v[66:69], v[120:123], v[50:65]
	ds_read_b64_tr_b16 v[120:121], v199 offset:0x2200
	ds_read_b64_tr_b16 v[122:123], v199 offset:0x2a00
	v_mfma_f32_32x32x16_bf16 v[2:17], v[104:107], v[124:127], v[2:17]
	ds_read_b64_tr_b16 v[124:125], v199 offset:0x3000
	ds_read_b64_tr_b16 v[126:127], v199 offset:0x3800
	ds_read_b64_tr_b16 v[224:225], v199 offset:0x3200
	ds_read_b64_tr_b16 v[226:227], v199 offset:0x3a00
	s_waitcnt lgkmcnt(0)
	v_mfma_f32_32x32x16_bf16 v[50:65], v[104:107], v[220:223], v[50:65]
	v_mfma_f32_32x32x16_bf16 v[2:17], v[108:111], v[116:119], v[2:17]
	ds_read_b64_tr_b16 v[116:117], v199 offset:0x400
	ds_read_b64_tr_b16 v[118:119], v199 offset:0xc00
	v_mfma_f32_32x32x16_bf16 v[50:65], v[108:111], v[120:123], v[50:65]
	ds_read_b64_tr_b16 v[120:121], v199 offset:0x600
	ds_read_b64_tr_b16 v[122:123], v199 offset:0xe00
	v_mfma_f32_32x32x16_bf16 v[2:17], v[112:115], v[124:127], v[2:17]
	ds_read_b64_tr_b16 v[124:125], v199 offset:0x1400
	ds_read_b64_tr_b16 v[126:127], v199 offset:0x1c00
	ds_read_b64_tr_b16 v[220:221], v199 offset:0x1600
	ds_read_b64_tr_b16 v[222:223], v199 offset:0x1e00
	s_waitcnt lgkmcnt(0)
	v_mfma_f32_32x32x16_bf16 v[50:65], v[112:115], v[224:227], v[50:65]
	v_mfma_f32_32x32x16_bf16 v[34:49], v[66:69], v[116:119], v[34:49]
	v_mfma_f32_32x32x16_bf16 v[18:33], v[66:69], v[120:123], v[18:33]
	ds_read_b64_tr_b16 v[66:67], v199 offset:0x2400
	ds_read_b64_tr_b16 v[68:69], v199 offset:0x2c00
	ds_read_b64_tr_b16 v[116:117], v199 offset:0x2600
	ds_read_b64_tr_b16 v[118:119], v199 offset:0x2e00
	ds_read_b64_tr_b16 v[120:121], v199 offset:0x3400
	ds_read_b64_tr_b16 v[122:123], v199 offset:0x3c00
	v_mfma_f32_32x32x16_bf16 v[34:49], v[104:107], v[124:127], v[34:49]
	ds_read_b64_tr_b16 v[124:125], v199 offset:0x3600
	ds_read_b64_tr_b16 v[126:127], v199 offset:0x3e00
	s_waitcnt lgkmcnt(0)
	v_mfma_f32_32x32x16_bf16 v[18:33], v[104:107], v[220:223], v[18:33]
	v_mfma_f32_32x32x16_bf16 v[34:49], v[108:111], v[66:69], v[34:49]
	s_cmp_le_i32 s89, s76
	v_mfma_f32_32x32x16_bf16 v[18:33], v[108:111], v[116:119], v[18:33]
	v_mfma_f32_32x32x16_bf16 v[34:49], v[112:115], v[120:123], v[34:49]
	v_mfma_f32_32x32x16_bf16 v[18:33], v[112:115], v[124:127], v[18:33]
	s_cbranch_scc1 .LBB0_232
	v_subrev_u32_e32 v66, 64, v216
	v_cmp_gt_u32_e32 vcc, 2.0, v66
	v_add_u32_e32 v66, 0xbfffffa0, v216
	s_nop 0
	v_cndmask_b32_e32 v86, v209, v86, vcc
	v_cmp_lt_u32_e32 vcc, s17, v66
	v_add_u32_e32 v66, 0xbfffffbf, v216
	s_nop 0
	v_cndmask_b32_e32 v70, v209, v70, vcc
	v_cmp_lt_u32_e32 vcc, s17, v66
	v_add_u32_e32 v66, 0xbfffff9f, v216
	s_nop 0
	v_cndmask_b32_e32 v87, v209, v87, vcc
	v_cmp_lt_u32_e32 vcc, s17, v66
	v_add_u32_e32 v66, 0xbfffffbe, v216
	s_nop 0
	v_cndmask_b32_e32 v71, v209, v71, vcc
	v_cmp_lt_u32_e32 vcc, s17, v66
	v_add_u32_e32 v66, 0xbfffff9e, v216
	s_nop 0
	v_cndmask_b32_e32 v88, v209, v88, vcc
	v_cmp_lt_u32_e32 vcc, s17, v66
	v_add_u32_e32 v66, 0xbfffffbd, v216
	s_nop 0
	v_cndmask_b32_e32 v72, v209, v72, vcc
	v_cmp_lt_u32_e32 vcc, s17, v66
	v_add_u32_e32 v66, 0xbfffff9d, v216
	s_nop 0
	v_cndmask_b32_e32 v89, v209, v89, vcc
	v_cmp_lt_u32_e32 vcc, s17, v66
	v_add_u32_e32 v66, 0xbfffffb8, v216
	s_nop 0
	v_cndmask_b32_e32 v73, v209, v73, vcc
	v_cmp_lt_u32_e32 vcc, s17, v66
	v_add_u32_e32 v66, 0xbfffff98, v216
	s_nop 0
	v_cndmask_b32_e32 v90, v209, v90, vcc
	v_cmp_lt_u32_e32 vcc, s17, v66
	v_add_u32_e32 v66, 0xbfffffb7, v216
	s_nop 0
	v_cndmask_b32_e32 v74, v209, v74, vcc
	v_cmp_lt_u32_e32 vcc, s17, v66
	v_add_u32_e32 v66, 0xbfffff97, v216
	s_nop 0
	v_cndmask_b32_e32 v91, v209, v91, vcc
	v_cmp_lt_u32_e32 vcc, s17, v66
	v_add_u32_e32 v66, 0xbfffffb6, v216
	s_nop 0
	v_cndmask_b32_e32 v75, v209, v75, vcc
	v_cmp_lt_u32_e32 vcc, s17, v66
	v_add_u32_e32 v66, 0xbfffff96, v216
	s_nop 0
	v_cndmask_b32_e32 v92, v209, v92, vcc
	v_cmp_lt_u32_e32 vcc, s17, v66
	v_add_u32_e32 v66, 0xbfffffb5, v216
	s_nop 0
	v_cndmask_b32_e32 v76, v209, v76, vcc
	v_cmp_lt_u32_e32 vcc, s17, v66
	v_add_u32_e32 v66, 0xbfffff95, v216
	s_nop 0
	v_cndmask_b32_e32 v93, v209, v93, vcc
	v_cmp_lt_u32_e32 vcc, s17, v66
	v_add_u32_e32 v66, 0xbfffffb0, v216
	s_nop 0
	v_cndmask_b32_e32 v77, v209, v77, vcc
	v_cmp_lt_u32_e32 vcc, s17, v66
	v_add_u32_e32 v66, 0xbfffff90, v216
	s_nop 0
	v_cndmask_b32_e32 v94, v209, v94, vcc
	v_cmp_lt_u32_e32 vcc, s17, v66
	v_add_u32_e32 v66, 0xbfffffaf, v216
	s_nop 0
	v_cndmask_b32_e32 v78, v209, v78, vcc
	v_cmp_lt_u32_e32 vcc, s17, v66
	v_add_u32_e32 v66, 0xbfffff8f, v216
	s_nop 0
	v_cndmask_b32_e32 v95, v209, v95, vcc
	v_cmp_lt_u32_e32 vcc, s17, v66
	v_add_u32_e32 v66, 0xbfffffae, v216
	s_nop 0
	v_cndmask_b32_e32 v79, v209, v79, vcc
	v_cmp_lt_u32_e32 vcc, s17, v66
	v_add_u32_e32 v66, 0xbfffff8e, v216
	s_nop 0
	v_cndmask_b32_e32 v96, v209, v96, vcc
	v_cmp_lt_u32_e32 vcc, s17, v66
	v_add_u32_e32 v66, 0xbfffffad, v216
	s_nop 0
	v_cndmask_b32_e32 v80, v209, v80, vcc
	v_cmp_lt_u32_e32 vcc, s17, v66
	v_add_u32_e32 v66, 0xbfffff8d, v216
	s_nop 0
	v_cndmask_b32_e32 v97, v209, v97, vcc
	v_cmp_lt_u32_e32 vcc, s17, v66
	v_add_u32_e32 v66, 0xbfffffa8, v216
	s_nop 0
	v_cndmask_b32_e32 v81, v209, v81, vcc
	v_cmp_lt_u32_e32 vcc, s17, v66
	v_add_u32_e32 v66, 0xbfffff88, v216
	s_nop 0
	v_cndmask_b32_e32 v98, v209, v98, vcc
	v_cmp_lt_u32_e32 vcc, s17, v66
	v_add_u32_e32 v66, 0xbfffffa7, v216
	s_nop 0
	v_cndmask_b32_e32 v82, v209, v82, vcc
	v_cmp_lt_u32_e32 vcc, s17, v66
	v_add_u32_e32 v66, 0xbfffff87, v216
	s_nop 0
	v_cndmask_b32_e32 v99, v209, v99, vcc
	v_cmp_lt_u32_e32 vcc, s17, v66
	v_add_u32_e32 v66, 0xbfffffa6, v216
	s_nop 0
	v_cndmask_b32_e32 v83, v209, v83, vcc
	v_cmp_lt_u32_e32 vcc, s17, v66
	v_add_u32_e32 v66, 0xbfffff86, v216
	s_nop 0
	v_cndmask_b32_e32 v100, v209, v100, vcc
	v_cmp_lt_u32_e32 vcc, s17, v66
	v_add_u32_e32 v66, 0xbfffffa5, v216
	s_nop 0
	v_cndmask_b32_e32 v84, v209, v84, vcc
	v_cmp_lt_u32_e32 vcc, s17, v66
	v_add_u32_e32 v66, 0xbfffff85, v216
	s_nop 0
	v_cndmask_b32_e32 v101, v209, v101, vcc
	v_cmp_lt_u32_e32 vcc, s17, v66
	s_nop 1
	v_cndmask_b32_e32 v85, v209, v85, vcc

; #define SBAR() __builtin_amdgcn_sched_barrier(0)
; __device__ __forceinline__ void partialSM(f32x16& p0, f32x16& p1, float& m_reg, float& mn, float& alpha) {
;     ...
;     if (__builtin_expect(__all((pmax - m_reg) * SCALE <= THR), 1)) { mn = m_reg; alpha = 1.f; }
;     else { mn = fmaxf(m_reg, pmax); alpha = __builtin_amdgcn_exp2f((m_reg - mn) * C2); m_reg = mn; }
;     const float mnL = -mn * C2;
;     for (int r = 0; r < 16; ++r) p0[r] = fmaf(p0[r], C2, mnL); for (int r = 0; r < 16; ++r) p1[r] = fmaf(p1[r], C2, mnL);
;     for (int r = 0; r < 16; ++r) p0[r] = __builtin_amdgcn_exp2f(p0[r]);
; }
; __device__ __forceinline__ void finishSM(f32x16& p0, f32x16& p1, float alpha, float& l_reg, bf16x8& pa0, bf16x8& pa1, bf16x8& pa2, bf16x8& pa3) {
;     for (int r = 0; r < 16; ++r) p1[r] = __builtin_amdgcn_exp2f(p1[r]);
; __device__ __forceinline__ void fox_block(const BlockRef& cur, const BlockRef& nxt, char* lds, char* cbcur, char* cbnxt, Seam& S) {
;     ...
;     for (int t = 1; t + 1 < NT; t += 2) {
;         HALF_STEP(pB0, pB1, mnB, alB, pA0, pA1, alA, t, 1, 0, 0);
;         HALF_STEP(pA0, pA1, mnA, alA, pB0, pB1, alB, t + 1, 0, 1, 1);
;     }
;     const bool even = (NT & 1) == 0;
;     if (even) { SBAR(); qkt<1>(pB0, pB1, K_lds, cbl + 8 * KBASE(NT - 1), r32, hi, S.qr); SBAR(); }
.LBB0_246:
	v_cndmask_b32_e64 v217, v167, v217, s[4:5]
	v_mul_f32_e32 v168, 0xbe0293ee, v217
	s_waitcnt vmcnt(0)
	v_mov_b32_e32 v178, v168
	v_fmamk_f32 v167, v114, 0x3e0293ee, v168
	v_fmamk_f32 v169, v115, 0x3e0293ee, v168
	v_fmamk_f32 v170, v116, 0x3e0293ee, v168
	v_fmamk_f32 v171, v117, 0x3e0293ee, v168
	v_fmamk_f32 v118, v118, 0x3e0293ee, v168
	v_fmamk_f32 v119, v119, 0x3e0293ee, v168
	v_fmamk_f32 v172, v120, 0x3e0293ee, v168
	v_fmamk_f32 v173, v121, 0x3e0293ee, v168
	v_fmamk_f32 v122, v122, 0x3e0293ee, v168
	v_fmamk_f32 v123, v123, 0x3e0293ee, v168
	v_fmamk_f32 v174, v124, 0x3e0293ee, v168
	v_fmamk_f32 v175, v125, 0x3e0293ee, v168
	v_fmamk_f32 v176, v126, 0x3e0293ee, v168
	v_fmamk_f32 v177, v127, 0x3e0293ee, v168
	v_fmamk_f32 v128, v128, 0x3e0293ee, v168
	v_fmac_f32_e32 v178, 0x3e0293ee, v129
	v_exp_f32_e32 v234, v167
	v_exp_f32_e32 v236, v169
	v_exp_f32_e32 v232, v170
	v_exp_f32_e32 v235, v171
	v_exp_f32_e32 v231, v118
	v_exp_f32_e32 v233, v119
	v_exp_f32_e32 v229, v172
	v_exp_f32_e32 v230, v173
	v_exp_f32_e32 v226, v122
	v_exp_f32_e32 v228, v123
	v_exp_f32_e32 v225, v174
	v_exp_f32_e32 v227, v175
	v_exp_f32_e32 v222, v176
	v_exp_f32_e32 v224, v177
	v_exp_f32_e32 v221, v128
	v_exp_f32_e32 v223, v178
	v_pk_fma_f32 v[126:127], v[98:99], s[16:17], v[168:169] op_sel_hi:[1,0,0]
	v_add_f32_e32 v98, v218, v219
	v_fmac_f32_e32 v98, v187, v214
	v_add_f32_e32 v214, v237, v238
	s_addk_i32 s89, 0xff80
	s_add_i32 s85, s85, 2
	v_pk_fma_f32 v[124:125], v[100:101], s[16:17], v[168:169] op_sel_hi:[1,0,0]
	v_pk_fma_f32 v[120:121], v[102:103], s[16:17], v[168:169] op_sel_hi:[1,0,0]
	v_pk_fma_f32 v[116:117], v[104:105], s[16:17], v[168:169] op_sel_hi:[1,0,0]
	v_pk_fma_f32 v[114:115], v[106:107], s[16:17], v[168:169] op_sel_hi:[1,0,0]
	v_pk_fma_f32 v[128:129], v[108:109], s[16:17], v[168:169] op_sel_hi:[1,0,0]
	v_pk_fma_f32 v[122:123], v[110:111], s[16:17], v[168:169] op_sel_hi:[1,0,0]
	v_pk_fma_f32 v[118:119], v[112:113], s[16:17], v[168:169] op_sel_hi:[1,0,0]
	v_fmac_f32_e32 v214, v98, v220
	v_add_u32_e32 v215, 0xfffffc00, v215
	s_cmp_ge_u32 s85, s77
	v_add_u32_e32 v216, 0x80, v216
	s_waitcnt lgkmcnt(0)
	s_cbranch_scc1 .Lattn_loop_exit
	v_mov_b32_e32 v187, v166
	s_branch .Lattn_loop_head
.Lattn_loop_exit:
	s_barrier
.LBB0_248:
	v_and_b32_e32 v1, 31, v0
	v_and_b32_e32 v201, 63, v0
	s_bitcmp0_b32 s84, 6
	s_cselect_b64 s[4:5], -1, 0
	s_and_b64 vcc, exec, s[4:5]
	s_cbranch_vccz .LBB0_250
	ds_read2_b64 v[82:85], v200 offset1:32
	ds_read_b128 v[98:101], v205 offset:49152
	ds_read_b128 v[102:105], v205 offset:49280
	s_waitcnt lgkmcnt(2)
	v_mov_b32_e32 v66, v82
	v_mov_b32_e32 v67, v83
	v_mov_b32_e32 v68, v82
	v_mov_b32_e32 v69, v83
	v_mov_b32_e32 v82, v84
	v_mov_b32_e32 v83, v85
	v_mfma_f32_32x32x16_bf16 v[66:81], v[66:69], v[162:165], 0
	s_nop 0
	v_mfma_f32_32x32x16_bf16 v[82:97], v[82:85], v[162:165], 0
	s_waitcnt lgkmcnt(1)
	v_mfma_f32_32x32x16_bf16 v[66:81], v[98:101], v[158:161], v[66:81]
	ds_read_b128 v[98:101], v205 offset:57344
	ds_read_b128 v[106:109], v205 offset:57472
	s_waitcnt lgkmcnt(1)
	v_mfma_f32_32x32x16_bf16 v[82:97], v[98:101], v[158:161], v[82:97]
	ds_read_b128 v[98:101], v206 offset:49152
	ds_read_b128 v[110:113], v206 offset:49280
	s_waitcnt lgkmcnt(1)
	v_mfma_f32_32x32x16_bf16 v[66:81], v[98:101], v[154:157], v[66:81]
	ds_read_b128 v[98:101], v206 offset:57344
	ds_read_b128 v[158:161], v206 offset:57472
	s_waitcnt lgkmcnt(1)
	v_mfma_f32_32x32x16_bf16 v[82:97], v[98:101], v[154:157], v[82:97]
	ds_read_b128 v[98:101], v207 offset:49152
	ds_read_b128 v[154:157], v207 offset:49280
	s_waitcnt lgkmcnt(1)
	v_mfma_f32_32x32x16_bf16 v[66:81], v[98:101], v[150:153], v[66:81]
	ds_read_b128 v[98:101], v207 offset:57344
	ds_read_b128 v[168:171], v207 offset:57472
	s_waitcnt lgkmcnt(1)
	v_mfma_f32_32x32x16_bf16 v[82:97], v[98:101], v[150:153], v[82:97]
	ds_read_b128 v[98:101], v208 offset:49152
	ds_read_b128 v[150:153], v208 offset:49280
	s_waitcnt lgkmcnt(1)
	v_mfma_f32_32x32x16_bf16 v[66:81], v[98:101], v[146:149], v[66:81]
	ds_read_b128 v[98:101], v208 offset:57344
	ds_read_b128 v[172:175], v208 offset:57472
	s_waitcnt lgkmcnt(1)
	v_mfma_f32_32x32x16_bf16 v[82:97], v[98:101], v[146:149], v[82:97]
	v_mfma_f32_32x32x16_bf16 v[66:81], v[102:105], v[142:145], v[66:81]
	v_mfma_f32_32x32x16_bf16 v[82:97], v[106:109], v[142:145], v[82:97]
	v_mfma_f32_32x32x16_bf16 v[66:81], v[110:113], v[138:141], v[66:81]
	v_mfma_f32_32x32x16_bf16 v[82:97], v[158:161], v[138:141], v[82:97]
	v_mfma_f32_32x32x16_bf16 v[66:81], v[154:157], v[134:137], v[66:81]
	v_mfma_f32_32x32x16_bf16 v[82:97], v[168:171], v[134:137], v[82:97]
	v_mfma_f32_32x32x16_bf16 v[66:81], v[150:153], v[130:133], v[66:81]
	s_waitcnt lgkmcnt(0)
	v_mfma_f32_32x32x16_bf16 v[82:97], v[172:175], v[130:133], v[82:97]

; #define PG8_STAGE(bufoff, gbase, voff) do { _Pragma("unroll") for (int _i = 0; _i < 2; ++_i) \
;         __builtin_amdgcn_global_load_lds((const unsigned*)((const char*)(gbase) + (voff)[_i]), (PG8_LAS unsigned*)(lds + (bufoff) + ldsw + _i * 8192), 16, 0, 0); } while (0)
; #define PG8_LDA(dst, b, h) do { _Pragma("unroll") for (int m = 0; m < 4; ++m) _Pragma("unroll") for (int k = 0; k < 2; ++k) dst[m][k] = *(const PG8_LAS bf16x8*)(lds + PG8_SA(b, h) + aoff + m * 2048 + k * 1024); } while (0)
; #define PG8_LDB(dst, b, h) do { _Pragma("unroll") for (int n = 0; n < 2; ++n) _Pragma("unroll") for (int k = 0; k < 2; ++k) dst[n][k] = *(const PG8_LAS bf16x8*)(lds + PG8_SB(b, h) + boff + n * 2048 + k * 1024); } while (0)
; #define PG8_MMA(ai, bj, At, Bt) do { __builtin_amdgcn_s_setprio(1); _Pragma("unroll") for (int m = 0; m < 4; ++m) _Pragma("unroll") for (int n = 0; n < 2; ++n) _Pragma("unroll") for (int k = 0; k < 2; ++k) \
;         acc[ai][bj][m][n] = __builtin_amdgcn_mfma_f32_16x16x32_bf16(Bt[n][k], At[m][k], acc[ai][bj][m][n], 0, 0, 0); __builtin_amdgcn_s_setprio(0); } while (0)
; #define PG8_WAIT_V(n) asm volatile("s_waitcnt vmcnt(" #n ")" ::: "memory")
; #define PG8_WAIT_L(n) asm volatile("s_waitcnt lgkmcnt(" #n ")" ::: "memory")
; #define PG8_BAR __builtin_amdgcn_s_barrier()
; template <class Epi, class Sched, bool ALIGN_EPI = false, bool SP2 = false>
; __device__ __forceinline__ void gemm_phase(PG8_LAS unsigned char* lds, const Gemm g, const Sched& S, const Epi& E) {
;     ...
;             const char* a1 = cA + (size_t)(t + 1) * kstep;
;             const char* a2 = last ? nA : cA + (size_t)(t + 2) * kstep; const char* b2 = last ? nB : cB + (size_t)(t + 2) * kstep;
;             const char* a3 = a2 + kstep; const char* b3 = b2 + kstep;
;             if (last && has_next) S.a_ready(nxt);
;             if constexpr (SP2) {
;             PG8_LDB(B0, 0, 0); PG8_LDB(B1, 0, 1); PG8_SCHED; PG8_LDA(At, 0, 0); PG8_STAGE(PG8_SA(1, 1), a1 + hstep, voffA);
;             PG8_WAIT_V(8); PG8_WAIT_L(0); PG8_BAR; PG8_MMA(0, 0, At, B0); PG8_MMA(0, 1, At, B1); PG8_BAR; PG8_SCHED;
;             PG8_LDA(At, 0, 1); PG8_STAGE(PG8_SB(0, 0), b2, voffB); PG8_STAGE(PG8_SB(0, 1), b2 + hstep, voffB); PG8_STAGE(PG8_SA(0, 0), a2, voffA);
;             PG8_WAIT_V(8); PG8_WAIT_L(0); PG8_BAR; PG8_MMA(1, 0, At, B0); PG8_MMA(1, 1, At, B1); PG8_BAR; PG8_SCHED;
.LBB0_396:
	ds_read_b128 v[98:101], v172
	ds_read_b128 v[106:109], v172 offset:1024
	ds_read_b128 v[114:117], v172 offset:2048
	ds_read_b128 v[118:121], v172 offset:3072
	ds_read_b128 v[164:167], v173
	ds_read_b128 v[176:179], v173 offset:1024
	ds_read_b128 v[180:183], v173 offset:2048
	ds_read_b128 v[184:187], v173 offset:3072
	s_add_u32 s58, s56, 0xfffc0080
	s_addc_u32 s59, s57, -1
	s_cmp_eq_u32 s86, 12
	s_cselect_b32 s63, s43, s59
	s_cselect_b32 s62, s82, s58
	s_cselect_b32 s59, s23, s85
	s_cselect_b32 s58, s83, s84
	v_lshl_add_u64 v[168:169], s[56:57], 0, v[156:157]
	s_add_i32 m0, s55, 0xc000
	ds_read_b128 v[188:191], v174
	ds_read_b128 v[192:195], v174 offset:1024
	ds_read_b128 v[196:199], v174 offset:2048
	ds_read_b128 v[200:203], v174 offset:3072
	ds_read_b128 v[204:207], v174 offset:4096
	ds_read_b128 v[208:211], v174 offset:5120
	ds_read_b128 v[212:215], v174 offset:6144
	ds_read_b128 v[216:219], v174 offset:7168
	global_load_lds_dwordx4 v[168:169], off
	v_lshl_add_u64 v[168:169], s[56:57], 0, v[158:159]
	s_add_i32 m0, s55, 0xe000
	s_nop 0
	global_load_lds_dwordx4 v[168:169], off
	s_waitcnt vmcnt(8)
	s_waitcnt lgkmcnt(0)
	s_barrier
	s_waitcnt lgkmcnt(0)
	v_mfma_f32_16x16x32_bf16 v[142:145], v[98:101], v[188:191], v[142:145]
	v_mfma_f32_16x16x32_bf16 v[138:141], v[114:117], v[188:191], v[138:141]
	v_mfma_f32_16x16x32_bf16 v[126:129], v[98:101], v[196:199], v[126:129]
	v_mfma_f32_16x16x32_bf16 v[122:125], v[114:117], v[196:199], v[122:125]
	v_mfma_f32_16x16x32_bf16 v[94:97], v[98:101], v[204:207], v[94:97]
	v_mfma_f32_16x16x32_bf16 v[90:93], v[114:117], v[204:207], v[90:93]
	v_mfma_f32_16x16x32_bf16 v[78:81], v[98:101], v[212:215], v[78:81]
	v_mfma_f32_16x16x32_bf16 v[74:77], v[114:117], v[212:215], v[74:77]
	v_mfma_f32_16x16x32_bf16 v[142:145], v[106:109], v[192:195], v[142:145]
	v_mfma_f32_16x16x32_bf16 v[138:141], v[118:121], v[192:195], v[138:141]
	v_mfma_f32_16x16x32_bf16 v[126:129], v[106:109], v[200:203], v[126:129]
	v_mfma_f32_16x16x32_bf16 v[122:125], v[118:121], v[200:203], v[122:125]
	v_mfma_f32_16x16x32_bf16 v[94:97], v[106:109], v[208:211], v[94:97]
	v_mfma_f32_16x16x32_bf16 v[90:93], v[118:121], v[208:211], v[90:93]
	v_mfma_f32_16x16x32_bf16 v[78:81], v[106:109], v[216:219], v[78:81]
	v_mfma_f32_16x16x32_bf16 v[74:77], v[118:121], v[216:219], v[74:77]
	v_mfma_f32_16x16x32_bf16 v[134:137], v[164:167], v[188:191], v[134:137]
	v_mfma_f32_16x16x32_bf16 v[130:133], v[180:183], v[188:191], v[130:133]
	v_mfma_f32_16x16x32_bf16 v[110:113], v[164:167], v[196:199], v[110:113]
	v_mfma_f32_16x16x32_bf16 v[102:105], v[180:183], v[196:199], v[102:105]
	v_mfma_f32_16x16x32_bf16 v[86:89], v[164:167], v[204:207], v[86:89]
	v_mfma_f32_16x16x32_bf16 v[82:85], v[180:183], v[204:207], v[82:85]
	v_mfma_f32_16x16x32_bf16 v[70:73], v[164:167], v[212:215], v[70:73]
	v_mfma_f32_16x16x32_bf16 v[66:69], v[180:183], v[212:215], v[66:69]
	v_mfma_f32_16x16x32_bf16 v[134:137], v[176:179], v[192:195], v[134:137]
	v_mfma_f32_16x16x32_bf16 v[130:133], v[184:187], v[192:195], v[130:133]
	v_mfma_f32_16x16x32_bf16 v[110:113], v[176:179], v[200:203], v[110:113]
	v_mfma_f32_16x16x32_bf16 v[102:105], v[184:187], v[200:203], v[102:105]
	v_mfma_f32_16x16x32_bf16 v[86:89], v[176:179], v[208:211], v[86:89]
	v_mfma_f32_16x16x32_bf16 v[82:85], v[184:187], v[208:211], v[82:85]
	v_mfma_f32_16x16x32_bf16 v[70:73], v[176:179], v[216:219], v[70:73]
	v_mfma_f32_16x16x32_bf16 v[66:69], v[184:187], v[216:219], v[66:69]
	s_barrier
	s_add_i32 s87, s75, s67
	v_lshl_add_u64 v[168:169], s[58:59], 0, v[148:149]
	s_mov_b32 m0, s87
	ds_read_b128 v[188:191], v174 offset:16384
	ds_read_b128 v[192:195], v174 offset:17408
	ds_read_b128 v[196:199], v174 offset:18432
	ds_read_b128 v[200:203], v174 offset:19456
	ds_read_b128 v[204:207], v174 offset:20480
	ds_read_b128 v[208:211], v174 offset:21504
	ds_read_b128 v[212:215], v174 offset:22528
	ds_read_b128 v[216:219], v174 offset:23552
	global_load_lds_dwordx4 v[168:169], off
	s_add_i32 m0, s87, 0x2000
	s_add_u32 s88, s58, 0x40000
	v_lshl_add_u64 v[220:221], s[58:59], 0, v[152:153]
	s_addc_u32 s89, s59, 0
	s_add_i32 s87, s76, s67
	global_load_lds_dwordx4 v[220:221], off
	v_lshl_add_u64 v[222:223], s[88:89], 0, v[148:149]
	s_mov_b32 m0, s87
	v_lshl_add_u64 v[224:225], s[62:63], 0, v[150:151]
	global_load_lds_dwordx4 v[222:223], off
	v_lshl_add_u64 v[222:223], s[88:89], 0, v[152:153]
	s_add_i32 m0, s87, 0x2000
	s_nop 0
	global_load_lds_dwordx4 v[222:223], off
	v_lshl_add_u64 v[222:223], s[62:63], 0, v[146:147]
	s_mov_b32 m0, s55
	s_nop 0
	global_load_lds_dwordx4 v[222:223], off
	s_mov_b32 m0, s68
	s_nop 0
	global_load_lds_dwordx4 v[224:225], off
	s_waitcnt vmcnt(8)
	s_waitcnt lgkmcnt(0)
	s_barrier
; #define PG8_STAGE(bufoff, gbase, voff) do { _Pragma("unroll") for (int _i = 0; _i < 2; ++_i) \
;         __builtin_amdgcn_global_load_lds((const unsigned*)((const char*)(gbase) + (voff)[_i]), (PG8_LAS unsigned*)(lds + (bufoff) + ldsw + _i * 8192), 16, 0, 0); } while (0)
; #define PG8_LDA(dst, b, h) do { _Pragma("unroll") for (int m = 0; m < 4; ++m) _Pragma("unroll") for (int k = 0; k < 2; ++k) dst[m][k] = *(const PG8_LAS bf16x8*)(lds + PG8_SA(b, h) + aoff + m * 2048 + k * 1024); } while (0)
; #define PG8_LDB(dst, b, h) do { _Pragma("unroll") for (int n = 0; n < 2; ++n) _Pragma("unroll") for (int k = 0; k < 2; ++k) dst[n][k] = *(const PG8_LAS bf16x8*)(lds + PG8_SB(b, h) + boff + n * 2048 + k * 1024); } while (0)
; #define PG8_MMA(ai, bj, At, Bt) do { __builtin_amdgcn_s_setprio(1); _Pragma("unroll") for (int m = 0; m < 4; ++m) _Pragma("unroll") for (int n = 0; n < 2; ++n) _Pragma("unroll") for (int k = 0; k < 2; ++k) \
;         acc[ai][bj][m][n] = __builtin_amdgcn_mfma_f32_16x16x32_bf16(Bt[n][k], At[m][k], acc[ai][bj][m][n], 0, 0, 0); __builtin_amdgcn_s_setprio(0); } while (0)
; #define PG8_WAIT_V(n) asm volatile("s_waitcnt vmcnt(" #n ")" ::: "memory")
; #define PG8_WAIT_L(n) asm volatile("s_waitcnt lgkmcnt(" #n ")" ::: "memory")
; #define PG8_BAR __builtin_amdgcn_s_barrier()
; #define PG8_SCHED __builtin_amdgcn_sched_barrier(0)
; template <class Epi, class Sched, bool ALIGN_EPI = false, bool SP2 = false>
; __device__ __forceinline__ void gemm_phase(PG8_LAS unsigned char* lds, const Gemm g, const Sched& S, const Epi& E) {
;     ...
;             PG8_WAIT_V(8); PG8_WAIT_L(0); PG8_BAR; PG8_MMA(1, 0, At, B0); PG8_MMA(1, 1, At, B1); PG8_BAR; PG8_SCHED;
;             PG8_LDB(B0, 1, 0); PG8_LDB(B1, 1, 1); PG8_SCHED; PG8_LDA(At, 1, 0); PG8_STAGE(PG8_SA(0, 1), a2 + hstep, voffA);
;             PG8_WAIT_V(8); PG8_WAIT_L(0); PG8_BAR; PG8_MMA(0, 0, At, B0); PG8_MMA(0, 1, At, B1); PG8_BAR; PG8_SCHED;
	s_waitcnt lgkmcnt(0)
	v_mfma_f32_16x16x32_bf16 v[62:65], v[98:101], v[188:191], v[62:65]
	v_mfma_f32_16x16x32_bf16 v[58:61], v[114:117], v[188:191], v[58:61]
	v_mfma_f32_16x16x32_bf16 v[46:49], v[98:101], v[196:199], v[46:49]
	v_mfma_f32_16x16x32_bf16 v[42:45], v[114:117], v[196:199], v[42:45]
	v_mfma_f32_16x16x32_bf16 v[30:33], v[98:101], v[204:207], v[30:33]
	v_mfma_f32_16x16x32_bf16 v[26:29], v[114:117], v[204:207], v[26:29]
	v_mfma_f32_16x16x32_bf16 v[14:17], v[98:101], v[212:215], v[14:17]
	v_mfma_f32_16x16x32_bf16 v[10:13], v[114:117], v[212:215], v[10:13]
	v_mfma_f32_16x16x32_bf16 v[62:65], v[106:109], v[192:195], v[62:65]
	v_mfma_f32_16x16x32_bf16 v[58:61], v[118:121], v[192:195], v[58:61]
	v_mfma_f32_16x16x32_bf16 v[46:49], v[106:109], v[200:203], v[46:49]
	v_mfma_f32_16x16x32_bf16 v[42:45], v[118:121], v[200:203], v[42:45]
	v_mfma_f32_16x16x32_bf16 v[30:33], v[106:109], v[208:211], v[30:33]
	v_mfma_f32_16x16x32_bf16 v[26:29], v[118:121], v[208:211], v[26:29]
	v_mfma_f32_16x16x32_bf16 v[14:17], v[106:109], v[216:219], v[14:17]
	v_mfma_f32_16x16x32_bf16 v[10:13], v[118:121], v[216:219], v[10:13]
	v_mfma_f32_16x16x32_bf16 v[54:57], v[164:167], v[188:191], v[54:57]
	v_mfma_f32_16x16x32_bf16 v[50:53], v[180:183], v[188:191], v[50:53]
	v_mfma_f32_16x16x32_bf16 v[38:41], v[164:167], v[196:199], v[38:41]
	v_mfma_f32_16x16x32_bf16 v[34:37], v[180:183], v[196:199], v[34:37]
	v_mfma_f32_16x16x32_bf16 v[22:25], v[164:167], v[204:207], v[22:25]
	v_mfma_f32_16x16x32_bf16 v[18:21], v[180:183], v[204:207], v[18:21]
	v_mfma_f32_16x16x32_bf16 v[6:9], v[164:167], v[212:215], v[6:9]
	v_mfma_f32_16x16x32_bf16 v[2:5], v[180:183], v[212:215], v[2:5]
	v_mfma_f32_16x16x32_bf16 v[54:57], v[176:179], v[192:195], v[54:57]
	v_mfma_f32_16x16x32_bf16 v[50:53], v[184:187], v[192:195], v[50:53]
	v_mfma_f32_16x16x32_bf16 v[38:41], v[176:179], v[200:203], v[38:41]
	v_mfma_f32_16x16x32_bf16 v[34:37], v[184:187], v[200:203], v[34:37]
	v_mfma_f32_16x16x32_bf16 v[22:25], v[176:179], v[208:211], v[22:25]
	v_mfma_f32_16x16x32_bf16 v[18:21], v[184:187], v[208:211], v[18:21]
	v_mfma_f32_16x16x32_bf16 v[6:9], v[176:179], v[216:219], v[6:9]
	v_mfma_f32_16x16x32_bf16 v[2:5], v[184:187], v[216:219], v[2:5]
	s_barrier
	s_add_i32 s87, 0, 0x18000
	s_add_i32 s88, 0, 0x1c000
	v_add_u32_e32 v118, s87, v170
	v_add_u32_e32 v154, s88, v170
	ds_read_b128 v[98:101], v118
	ds_read_b128 v[106:109], v118 offset:1024
	ds_read_b128 v[114:117], v118 offset:2048
	ds_read_b128 v[118:121], v118 offset:3072
	ds_read_b128 v[164:167], v154
	ds_read_b128 v[176:179], v154 offset:1024
	ds_read_b128 v[180:183], v154 offset:2048
	ds_read_b128 v[184:187], v154 offset:3072
	s_add_u32 s62, s62, 0x40000
	s_addc_u32 s63, s63, 0
	s_mov_b32 m0, s69
	v_lshl_add_u64 v[226:227], s[62:63], 0, v[146:147]
	ds_read_b128 v[188:191], v174 offset:32768
	ds_read_b128 v[192:195], v174 offset:33792
	ds_read_b128 v[196:199], v174 offset:34816
	ds_read_b128 v[200:203], v174 offset:35840
	ds_read_b128 v[204:207], v174 offset:36864
	ds_read_b128 v[208:211], v174 offset:37888
	ds_read_b128 v[212:215], v174 offset:38912
	ds_read_b128 v[216:219], v174 offset:39936
	global_load_lds_dwordx4 v[226:227], off
	v_lshl_add_u64 v[226:227], s[62:63], 0, v[150:151]
	s_mov_b32 m0, s70
	s_nop 0
	global_load_lds_dwordx4 v[226:227], off
	s_waitcnt vmcnt(8)
	s_waitcnt lgkmcnt(0)
	s_barrier
	s_waitcnt lgkmcnt(0)
	v_mfma_f32_16x16x32_bf16 v[142:145], v[98:101], v[188:191], v[142:145]
	v_mfma_f32_16x16x32_bf16 v[138:141], v[114:117], v[188:191], v[138:141]
	v_mfma_f32_16x16x32_bf16 v[126:129], v[98:101], v[196:199], v[126:129]
	v_mfma_f32_16x16x32_bf16 v[122:125], v[114:117], v[196:199], v[122:125]
	v_mfma_f32_16x16x32_bf16 v[94:97], v[98:101], v[204:207], v[94:97]
	v_mfma_f32_16x16x32_bf16 v[90:93], v[114:117], v[204:207], v[90:93]
	v_mfma_f32_16x16x32_bf16 v[78:81], v[98:101], v[212:215], v[78:81]
	v_mfma_f32_16x16x32_bf16 v[74:77], v[114:117], v[212:215], v[74:77]
	v_mfma_f32_16x16x32_bf16 v[142:145], v[106:109], v[192:195], v[142:145]
	v_mfma_f32_16x16x32_bf16 v[138:141], v[118:121], v[192:195], v[138:141]
	v_mfma_f32_16x16x32_bf16 v[126:129], v[106:109], v[200:203], v[126:129]
	v_mfma_f32_16x16x32_bf16 v[122:125], v[118:121], v[200:203], v[122:125]
	v_mfma_f32_16x16x32_bf16 v[94:97], v[106:109], v[208:211], v[94:97]
	v_mfma_f32_16x16x32_bf16 v[90:93], v[118:121], v[208:211], v[90:93]
	v_mfma_f32_16x16x32_bf16 v[78:81], v[106:109], v[216:219], v[78:81]
	v_mfma_f32_16x16x32_bf16 v[74:77], v[118:121], v[216:219], v[74:77]
	v_mfma_f32_16x16x32_bf16 v[134:137], v[164:167], v[188:191], v[134:137]
	v_mfma_f32_16x16x32_bf16 v[130:133], v[180:183], v[188:191], v[130:133]
	v_mfma_f32_16x16x32_bf16 v[110:113], v[164:167], v[196:199], v[110:113]
	v_mfma_f32_16x16x32_bf16 v[102:105], v[180:183], v[196:199], v[102:105]
	v_mfma_f32_16x16x32_bf16 v[86:89], v[164:167], v[204:207], v[86:89]
	v_mfma_f32_16x16x32_bf16 v[82:85], v[180:183], v[204:207], v[82:85]
	v_mfma_f32_16x16x32_bf16 v[70:73], v[164:167], v[212:215], v[70:73]
	v_mfma_f32_16x16x32_bf16 v[66:69], v[180:183], v[212:215], v[66:69]
	v_mfma_f32_16x16x32_bf16 v[134:137], v[176:179], v[192:195], v[134:137]
	v_mfma_f32_16x16x32_bf16 v[130:133], v[184:187], v[192:195], v[130:133]
	v_mfma_f32_16x16x32_bf16 v[110:113], v[176:179], v[200:203], v[110:113]
	v_mfma_f32_16x16x32_bf16 v[102:105], v[184:187], v[200:203], v[102:105]
	v_mfma_f32_16x16x32_bf16 v[86:89], v[176:179], v[208:211], v[86:89]
	v_mfma_f32_16x16x32_bf16 v[82:85], v[184:187], v[208:211], v[82:85]
	v_mfma_f32_16x16x32_bf16 v[70:73], v[176:179], v[216:219], v[70:73]
	v_mfma_f32_16x16x32_bf16 v[66:69], v[184:187], v[216:219], v[66:69]
	s_barrier
; #define PG8_STAGE(bufoff, gbase, voff) do { _Pragma("unroll") for (int _i = 0; _i < 2; ++_i) \
;         __builtin_amdgcn_global_load_lds((const unsigned*)((const char*)(gbase) + (voff)[_i]), (PG8_LAS unsigned*)(lds + (bufoff) + ldsw + _i * 8192), 16, 0, 0); } while (0)
; #define PG8_LDA(dst, b, h) do { _Pragma("unroll") for (int m = 0; m < 4; ++m) _Pragma("unroll") for (int k = 0; k < 2; ++k) dst[m][k] = *(const PG8_LAS bf16x8*)(lds + PG8_SA(b, h) + aoff + m * 2048 + k * 1024); } while (0)
; #define PG8_MMA(ai, bj, At, Bt) do { __builtin_amdgcn_s_setprio(1); _Pragma("unroll") for (int m = 0; m < 4; ++m) _Pragma("unroll") for (int n = 0; n < 2; ++n) _Pragma("unroll") for (int k = 0; k < 2; ++k) \
;         acc[ai][bj][m][n] = __builtin_amdgcn_mfma_f32_16x16x32_bf16(Bt[n][k], At[m][k], acc[ai][bj][m][n], 0, 0, 0); __builtin_amdgcn_s_setprio(0); } while (0)
; #define PG8_WAIT_V(n) asm volatile("s_waitcnt vmcnt(" #n ")" ::: "memory")
; #define PG8_WAIT_L(n) asm volatile("s_waitcnt lgkmcnt(" #n ")" ::: "memory")
; #define PG8_BAR __builtin_amdgcn_s_barrier()
; #define PG8_SCHED __builtin_amdgcn_sched_barrier(0)
; template <class Epi, class Sched, bool ALIGN_EPI = false, bool SP2 = false>
; __device__ __forceinline__ void gemm_phase(PG8_LAS unsigned char* lds, const Gemm g, const Sched& S, const Epi& E) {
;     ...
;         for (int t = 0; t < nt; t += 2) {
;             if constexpr (Epi::HAS_MID) { if (t == Epi::MID_T) E.mid(acc, cur, wr, wc, fr, fq); }
;             const bool last = (t == nt - 2);
;     ...
;             PG8_LDA(At, 1, 1); PG8_STAGE(PG8_SB(1, 0), b3, voffB); PG8_STAGE(PG8_SB(1, 1), b3 + hstep, voffB); PG8_STAGE(PG8_SA(1, 0), a3, voffA);
;             PG8_WAIT_V(8); PG8_WAIT_L(0); PG8_BAR; PG8_MMA(1, 0, At, B0); PG8_MMA(1, 1, At, B1); PG8_BAR; PG8_SCHED;
	s_add_i32 s62, s87, s67
	v_lshl_add_u64 v[168:169], v[168:169], 0, s[12:13]
	s_mov_b32 m0, s62
	ds_read_b128 v[188:191], v174 offset:49152
	ds_read_b128 v[192:195], v174 offset:50176
	ds_read_b128 v[196:199], v174 offset:51200
	ds_read_b128 v[200:203], v174 offset:52224
	ds_read_b128 v[204:207], v174 offset:53248
	ds_read_b128 v[208:211], v174 offset:54272
	ds_read_b128 v[212:215], v174 offset:55296
	ds_read_b128 v[216:219], v174 offset:56320
	global_load_lds_dwordx4 v[168:169], off
	s_add_i32 m0, s62, 0x2000
	s_add_u32 s58, s58, 0x40080
	v_lshl_add_u64 v[168:169], v[220:221], 0, s[12:13]
	s_addc_u32 s59, s59, 0
	s_add_i32 s62, s88, s67
	global_load_lds_dwordx4 v[168:169], off
	v_lshl_add_u64 v[168:169], s[58:59], 0, v[148:149]
	s_mov_b32 m0, s62
	s_nop 0
	global_load_lds_dwordx4 v[168:169], off
	v_lshl_add_u64 v[168:169], s[58:59], 0, v[152:153]
	s_add_i32 m0, s62, 0x2000
	s_nop 0
	global_load_lds_dwordx4 v[168:169], off
	v_lshl_add_u64 v[168:169], v[222:223], 0, s[12:13]
	s_mov_b32 m0, s72
	s_nop 0
	global_load_lds_dwordx4 v[168:169], off
	v_lshl_add_u64 v[168:169], v[224:225], 0, s[12:13]
	s_mov_b32 m0, s73
	s_nop 0
	global_load_lds_dwordx4 v[168:169], off
	s_waitcnt vmcnt(8)
	s_waitcnt lgkmcnt(0)
	s_barrier
	s_waitcnt lgkmcnt(0)
	v_mfma_f32_16x16x32_bf16 v[62:65], v[98:101], v[188:191], v[62:65]
	v_mfma_f32_16x16x32_bf16 v[58:61], v[114:117], v[188:191], v[58:61]
	v_mfma_f32_16x16x32_bf16 v[46:49], v[98:101], v[196:199], v[46:49]
	v_mfma_f32_16x16x32_bf16 v[42:45], v[114:117], v[196:199], v[42:45]
	v_mfma_f32_16x16x32_bf16 v[30:33], v[98:101], v[204:207], v[30:33]
	v_mfma_f32_16x16x32_bf16 v[26:29], v[114:117], v[204:207], v[26:29]
	v_mfma_f32_16x16x32_bf16 v[14:17], v[98:101], v[212:215], v[14:17]
	v_mfma_f32_16x16x32_bf16 v[10:13], v[114:117], v[212:215], v[10:13]
	v_mfma_f32_16x16x32_bf16 v[62:65], v[106:109], v[192:195], v[62:65]
	v_mfma_f32_16x16x32_bf16 v[58:61], v[118:121], v[192:195], v[58:61]
	v_mfma_f32_16x16x32_bf16 v[46:49], v[106:109], v[200:203], v[46:49]
	v_mfma_f32_16x16x32_bf16 v[42:45], v[118:121], v[200:203], v[42:45]
	v_mfma_f32_16x16x32_bf16 v[30:33], v[106:109], v[208:211], v[30:33]
	v_mfma_f32_16x16x32_bf16 v[26:29], v[118:121], v[208:211], v[26:29]
	v_mfma_f32_16x16x32_bf16 v[14:17], v[106:109], v[216:219], v[14:17]
	v_mfma_f32_16x16x32_bf16 v[10:13], v[118:121], v[216:219], v[10:13]
	v_mfma_f32_16x16x32_bf16 v[54:57], v[164:167], v[188:191], v[54:57]
	v_mfma_f32_16x16x32_bf16 v[50:53], v[180:183], v[188:191], v[50:53]
	v_mfma_f32_16x16x32_bf16 v[38:41], v[164:167], v[196:199], v[38:41]
	v_mfma_f32_16x16x32_bf16 v[34:37], v[180:183], v[196:199], v[34:37]
	v_mfma_f32_16x16x32_bf16 v[22:25], v[164:167], v[204:207], v[22:25]
	v_mfma_f32_16x16x32_bf16 v[18:21], v[180:183], v[204:207], v[18:21]
	v_mfma_f32_16x16x32_bf16 v[6:9], v[164:167], v[212:215], v[6:9]
	v_mfma_f32_16x16x32_bf16 v[2:5], v[180:183], v[212:215], v[2:5]
	v_mfma_f32_16x16x32_bf16 v[54:57], v[176:179], v[192:195], v[54:57]
	v_mfma_f32_16x16x32_bf16 v[50:53], v[184:187], v[192:195], v[50:53]
	v_mfma_f32_16x16x32_bf16 v[38:41], v[176:179], v[200:203], v[38:41]
	v_mfma_f32_16x16x32_bf16 v[34:37], v[184:187], v[200:203], v[34:37]
	v_mfma_f32_16x16x32_bf16 v[22:25], v[176:179], v[208:211], v[22:25]
	v_mfma_f32_16x16x32_bf16 v[18:21], v[184:187], v[208:211], v[18:21]
	v_mfma_f32_16x16x32_bf16 v[6:9], v[176:179], v[216:219], v[6:9]
	v_mfma_f32_16x16x32_bf16 v[2:5], v[184:187], v[216:219], v[2:5]
	s_add_i32 s86, s86, 2
	s_add_u32 s56, s56, 0x100
	s_addc_u32 s57, s57, 0
	s_add_u32 s84, s84, 0x100
	s_addc_u32 s85, s85, 0
	s_cmp_gt_u32 s86, 13
	s_barrier
	s_cbranch_scc0 .LBB0_396
	s_and_b64 vcc, exec, s[14:15]
	s_cbranch_vccz .LBB0_399
	s_barrier

; #define PG8_STAGE(bufoff, gbase, voff) do { _Pragma("unroll") for (int _i = 0; _i < 2; ++_i) \
;         __builtin_amdgcn_global_load_lds((const unsigned*)((const char*)(gbase) + (voff)[_i]), (PG8_LAS unsigned*)(lds + (bufoff) + ldsw + _i * 8192), 16, 0, 0); } while (0)
; #define PG8_LDA(dst, b, h) do { _Pragma("unroll") for (int m = 0; m < 4; ++m) _Pragma("unroll") for (int k = 0; k < 2; ++k) dst[m][k] = *(const PG8_LAS bf16x8*)(lds + PG8_SA(b, h) + aoff + m * 2048 + k * 1024); } while (0)
; #define PG8_LDB(dst, b, h) do { _Pragma("unroll") for (int n = 0; n < 2; ++n) _Pragma("unroll") for (int k = 0; k < 2; ++k) dst[n][k] = *(const PG8_LAS bf16x8*)(lds + PG8_SB(b, h) + boff + n * 2048 + k * 1024); } while (0)
; #define PG8_MMA(ai, bj, At, Bt) do { __builtin_amdgcn_s_setprio(1); _Pragma("unroll") for (int m = 0; m < 4; ++m) _Pragma("unroll") for (int n = 0; n < 2; ++n) _Pragma("unroll") for (int k = 0; k < 2; ++k) \
;         acc[ai][bj][m][n] = __builtin_amdgcn_mfma_f32_16x16x32_bf16(Bt[n][k], At[m][k], acc[ai][bj][m][n], 0, 0, 0); __builtin_amdgcn_s_setprio(0); } while (0)
; #define PG8_WAIT_V(n) asm volatile("s_waitcnt vmcnt(" #n ")" ::: "memory")
; #define PG8_WAIT_L(n) asm volatile("s_waitcnt lgkmcnt(" #n ")" ::: "memory")
; #define PG8_BAR __builtin_amdgcn_s_barrier()
; template <class Epi, class Sched, bool ALIGN_EPI = false, bool SP2 = false>
; __device__ __forceinline__ void gemm_phase(PG8_LAS unsigned char* lds, const Gemm g, const Sched& S, const Epi& E) {
;     ...
;             const char* a1 = cA + (size_t)(t + 1) * kstep;
;             const char* a2 = last ? nA : cA + (size_t)(t + 2) * kstep; const char* b2 = last ? nB : cB + (size_t)(t + 2) * kstep;
;             const char* a3 = a2 + kstep; const char* b3 = b2 + kstep;
;             if (last && has_next) S.a_ready(nxt);
;             if constexpr (SP2) {
;             PG8_LDB(B0, 0, 0); PG8_LDB(B1, 0, 1); PG8_SCHED; PG8_LDA(At, 0, 0); PG8_STAGE(PG8_SA(1, 1), a1 + hstep, voffA);
;             PG8_WAIT_V(8); PG8_WAIT_L(0); PG8_BAR; PG8_MMA(0, 0, At, B0); PG8_MMA(0, 1, At, B1); PG8_BAR; PG8_SCHED;
;             PG8_LDA(At, 0, 1); PG8_STAGE(PG8_SB(0, 0), b2, voffB); PG8_STAGE(PG8_SB(0, 1), b2 + hstep, voffB); PG8_STAGE(PG8_SA(0, 0), a2, voffA);
;             PG8_WAIT_V(8); PG8_WAIT_L(0); PG8_BAR; PG8_MMA(1, 0, At, B0); PG8_MMA(1, 1, At, B1); PG8_BAR; PG8_SCHED;
.LBB0_475:
	v_add_u32_e32 v3, s82, v176
	ds_read_b128 v[134:137], v3
	ds_read_b128 v[138:141], v3 offset:1024
	ds_read_b128 v[142:145], v3 offset:2048
	ds_read_b128 v[146:149], v3 offset:3072
	v_add_u32_e32 v3, s83, v176
	s_add_u32 s64, s58, s62
	ds_read_b128 v[150:153], v3
	ds_read_b128 v[180:183], v3 offset:1024
	ds_read_b128 v[184:187], v3 offset:2048
	ds_read_b128 v[188:191], v3 offset:3072
	s_addc_u32 s65, s59, s63
	s_add_u32 s64, s64, 0x100
	s_addc_u32 s65, s65, 0
	s_add_u32 s93, s90, s62
	s_addc_u32 s94, s91, s63
	s_cmpk_eq_i32 s62, 0xf00
	s_cselect_b32 s67, s53, s65
	s_cselect_b32 s66, s84, s64
	s_cselect_b32 s65, s86, s94
	s_cselect_b32 s64, s87, s93
	v_lshl_add_u64 v[4:5], v[170:171], 0, s[62:63]
	s_add_i32 m0, s72, 0xc000
	ds_read_b128 v[192:195], v178
	ds_read_b128 v[196:199], v178 offset:1024
	ds_read_b128 v[200:203], v178 offset:2048
	ds_read_b128 v[204:207], v178 offset:3072
	ds_read_b128 v[208:211], v178 offset:4096
	ds_read_b128 v[212:215], v178 offset:5120
	ds_read_b128 v[216:219], v178 offset:6144
	ds_read_b128 v[220:223], v178 offset:7168
	global_load_lds_dwordx4 v[4:5], off
	v_lshl_add_u64 v[4:5], v[172:173], 0, s[62:63]
	s_add_i32 m0, s72, 0xe000
	s_nop 0
	global_load_lds_dwordx4 v[4:5], off
	s_waitcnt vmcnt(8)
	s_waitcnt lgkmcnt(0)
	s_barrier
	s_waitcnt lgkmcnt(0)
	v_mfma_f32_16x16x32_bf16 v[130:133], v[134:137], v[192:195], v[130:133]
	v_mfma_f32_16x16x32_bf16 v[126:129], v[142:145], v[192:195], v[126:129]
	v_mfma_f32_16x16x32_bf16 v[114:117], v[134:137], v[200:203], v[114:117]
	v_mfma_f32_16x16x32_bf16 v[110:113], v[142:145], v[200:203], v[110:113]
	v_mfma_f32_16x16x32_bf16 v[98:101], v[134:137], v[208:211], v[98:101]
	v_mfma_f32_16x16x32_bf16 v[94:97], v[142:145], v[208:211], v[94:97]
	v_mfma_f32_16x16x32_bf16 v[82:85], v[134:137], v[216:219], v[82:85]
	v_mfma_f32_16x16x32_bf16 v[78:81], v[142:145], v[216:219], v[78:81]
	v_mfma_f32_16x16x32_bf16 v[130:133], v[138:141], v[196:199], v[130:133]
	v_mfma_f32_16x16x32_bf16 v[126:129], v[146:149], v[196:199], v[126:129]
	v_mfma_f32_16x16x32_bf16 v[114:117], v[138:141], v[204:207], v[114:117]
	v_mfma_f32_16x16x32_bf16 v[110:113], v[146:149], v[204:207], v[110:113]
	v_mfma_f32_16x16x32_bf16 v[98:101], v[138:141], v[212:215], v[98:101]
	v_mfma_f32_16x16x32_bf16 v[94:97], v[146:149], v[212:215], v[94:97]
	v_mfma_f32_16x16x32_bf16 v[82:85], v[138:141], v[220:223], v[82:85]
	v_mfma_f32_16x16x32_bf16 v[78:81], v[146:149], v[220:223], v[78:81]
	v_mfma_f32_16x16x32_bf16 v[122:125], v[150:153], v[192:195], v[122:125]
	v_mfma_f32_16x16x32_bf16 v[118:121], v[184:187], v[192:195], v[118:121]
	v_mfma_f32_16x16x32_bf16 v[106:109], v[150:153], v[200:203], v[106:109]
	v_mfma_f32_16x16x32_bf16 v[102:105], v[184:187], v[200:203], v[102:105]
	v_mfma_f32_16x16x32_bf16 v[90:93], v[150:153], v[208:211], v[90:93]
	v_mfma_f32_16x16x32_bf16 v[86:89], v[184:187], v[208:211], v[86:89]
	v_mfma_f32_16x16x32_bf16 v[74:77], v[150:153], v[216:219], v[74:77]
	v_mfma_f32_16x16x32_bf16 v[70:73], v[184:187], v[216:219], v[70:73]
	v_mfma_f32_16x16x32_bf16 v[122:125], v[180:183], v[196:199], v[122:125]
	v_mfma_f32_16x16x32_bf16 v[118:121], v[188:191], v[196:199], v[118:121]
	v_mfma_f32_16x16x32_bf16 v[106:109], v[180:183], v[204:207], v[106:109]
	v_mfma_f32_16x16x32_bf16 v[102:105], v[188:191], v[204:207], v[102:105]
	v_mfma_f32_16x16x32_bf16 v[90:93], v[180:183], v[212:215], v[90:93]
	v_mfma_f32_16x16x32_bf16 v[86:89], v[188:191], v[212:215], v[86:89]
	v_mfma_f32_16x16x32_bf16 v[74:77], v[180:183], v[220:223], v[74:77]
	v_mfma_f32_16x16x32_bf16 v[70:73], v[188:191], v[220:223], v[70:73]
	s_barrier
	s_add_i32 s93, s82, s71
	v_lshl_add_u64 v[224:225], s[64:65], 0, v[156:157]
	s_mov_b32 m0, s93
	ds_read_b128 v[192:195], v178 offset:16384
	ds_read_b128 v[196:199], v178 offset:17408
	ds_read_b128 v[200:203], v178 offset:18432
	ds_read_b128 v[204:207], v178 offset:19456
	ds_read_b128 v[208:211], v178 offset:20480
	ds_read_b128 v[212:215], v178 offset:21504
	ds_read_b128 v[216:219], v178 offset:22528
	ds_read_b128 v[220:223], v178 offset:23552
	global_load_lds_dwordx4 v[224:225], off
	s_add_i32 m0, s93, 0x2000
	s_add_u32 s94, s64, 0x80000
	v_lshl_add_u64 v[226:227], s[64:65], 0, v[160:161]
	s_addc_u32 s95, s65, 0
	s_add_i32 s93, s83, s71
	global_load_lds_dwordx4 v[226:227], off
	v_lshl_add_u64 v[4:5], s[94:95], 0, v[156:157]
	s_mov_b32 m0, s93
	v_lshl_add_u64 v[228:229], s[66:67], 0, v[154:155]
	global_load_lds_dwordx4 v[4:5], off
	v_lshl_add_u64 v[4:5], s[94:95], 0, v[160:161]
	s_add_i32 m0, s93, 0x2000
	v_lshl_add_u64 v[230:231], s[66:67], 0, v[158:159]
	global_load_lds_dwordx4 v[4:5], off
	s_mov_b32 m0, s72
	s_nop 0
	global_load_lds_dwordx4 v[228:229], off
	s_mov_b32 m0, s73
	s_nop 0
	global_load_lds_dwordx4 v[230:231], off
	s_waitcnt vmcnt(8)
	s_waitcnt lgkmcnt(0)
	s_barrier
; #define PG8_STAGE(bufoff, gbase, voff) do { _Pragma("unroll") for (int _i = 0; _i < 2; ++_i) \
;         __builtin_amdgcn_global_load_lds((const unsigned*)((const char*)(gbase) + (voff)[_i]), (PG8_LAS unsigned*)(lds + (bufoff) + ldsw + _i * 8192), 16, 0, 0); } while (0)
; #define PG8_LDA(dst, b, h) do { _Pragma("unroll") for (int m = 0; m < 4; ++m) _Pragma("unroll") for (int k = 0; k < 2; ++k) dst[m][k] = *(const PG8_LAS bf16x8*)(lds + PG8_SA(b, h) + aoff + m * 2048 + k * 1024); } while (0)
; #define PG8_LDB(dst, b, h) do { _Pragma("unroll") for (int n = 0; n < 2; ++n) _Pragma("unroll") for (int k = 0; k < 2; ++k) dst[n][k] = *(const PG8_LAS bf16x8*)(lds + PG8_SB(b, h) + boff + n * 2048 + k * 1024); } while (0)
; #define PG8_MMA(ai, bj, At, Bt) do { __builtin_amdgcn_s_setprio(1); _Pragma("unroll") for (int m = 0; m < 4; ++m) _Pragma("unroll") for (int n = 0; n < 2; ++n) _Pragma("unroll") for (int k = 0; k < 2; ++k) \
;         acc[ai][bj][m][n] = __builtin_amdgcn_mfma_f32_16x16x32_bf16(Bt[n][k], At[m][k], acc[ai][bj][m][n], 0, 0, 0); __builtin_amdgcn_s_setprio(0); } while (0)
; #define PG8_WAIT_V(n) asm volatile("s_waitcnt vmcnt(" #n ")" ::: "memory")
; #define PG8_WAIT_L(n) asm volatile("s_waitcnt lgkmcnt(" #n ")" ::: "memory")
; #define PG8_BAR __builtin_amdgcn_s_barrier()
; #define PG8_SCHED __builtin_amdgcn_sched_barrier(0)
; template <class Epi, class Sched, bool ALIGN_EPI = false, bool SP2 = false>
; __device__ __forceinline__ void gemm_phase(PG8_LAS unsigned char* lds, const Gemm g, const Sched& S, const Epi& E) {
;     ...
;             PG8_WAIT_V(8); PG8_WAIT_L(0); PG8_BAR; PG8_MMA(1, 0, At, B0); PG8_MMA(1, 1, At, B1); PG8_BAR; PG8_SCHED;
;             PG8_LDB(B0, 1, 0); PG8_LDB(B1, 1, 1); PG8_SCHED; PG8_LDA(At, 1, 0); PG8_STAGE(PG8_SA(0, 1), a2 + hstep, voffA);
;             PG8_WAIT_V(8); PG8_WAIT_L(0); PG8_BAR; PG8_MMA(0, 0, At, B0); PG8_MMA(0, 1, At, B1); PG8_BAR; PG8_SCHED;
	s_waitcnt lgkmcnt(0)
	v_mfma_f32_16x16x32_bf16 v[66:69], v[134:137], v[192:195], v[66:69]
	v_mfma_f32_16x16x32_bf16 v[62:65], v[142:145], v[192:195], v[62:65]
	v_mfma_f32_16x16x32_bf16 v[50:53], v[134:137], v[200:203], v[50:53]
	v_mfma_f32_16x16x32_bf16 v[46:49], v[142:145], v[200:203], v[46:49]
	v_mfma_f32_16x16x32_bf16 v[34:37], v[134:137], v[208:211], v[34:37]
	v_mfma_f32_16x16x32_bf16 v[30:33], v[142:145], v[208:211], v[30:33]
	v_mfma_f32_16x16x32_bf16 v[18:21], v[134:137], v[216:219], v[18:21]
	v_mfma_f32_16x16x32_bf16 v[14:17], v[142:145], v[216:219], v[14:17]
	v_mfma_f32_16x16x32_bf16 v[66:69], v[138:141], v[196:199], v[66:69]
	v_mfma_f32_16x16x32_bf16 v[62:65], v[146:149], v[196:199], v[62:65]
	v_mfma_f32_16x16x32_bf16 v[50:53], v[138:141], v[204:207], v[50:53]
	v_mfma_f32_16x16x32_bf16 v[46:49], v[146:149], v[204:207], v[46:49]
	v_mfma_f32_16x16x32_bf16 v[34:37], v[138:141], v[212:215], v[34:37]
	v_mfma_f32_16x16x32_bf16 v[30:33], v[146:149], v[212:215], v[30:33]
	v_mfma_f32_16x16x32_bf16 v[18:21], v[138:141], v[220:223], v[18:21]
	v_mfma_f32_16x16x32_bf16 v[14:17], v[146:149], v[220:223], v[14:17]
	v_mfma_f32_16x16x32_bf16 v[58:61], v[150:153], v[192:195], v[58:61]
	v_mfma_f32_16x16x32_bf16 v[54:57], v[184:187], v[192:195], v[54:57]
	v_mfma_f32_16x16x32_bf16 v[42:45], v[150:153], v[200:203], v[42:45]
	v_mfma_f32_16x16x32_bf16 v[38:41], v[184:187], v[200:203], v[38:41]
	v_mfma_f32_16x16x32_bf16 v[26:29], v[150:153], v[208:211], v[26:29]
	v_mfma_f32_16x16x32_bf16 v[22:25], v[184:187], v[208:211], v[22:25]
	v_mfma_f32_16x16x32_bf16 v[10:13], v[150:153], v[216:219], v[10:13]
	v_mfma_f32_16x16x32_bf16 v[4:7], v[184:187], v[216:219], v[6:9]
	v_mfma_f32_16x16x32_bf16 v[58:61], v[180:183], v[196:199], v[58:61]
	v_mfma_f32_16x16x32_bf16 v[54:57], v[188:191], v[196:199], v[54:57]
	v_mfma_f32_16x16x32_bf16 v[42:45], v[180:183], v[204:207], v[42:45]
	v_mfma_f32_16x16x32_bf16 v[38:41], v[188:191], v[204:207], v[38:41]
	v_mfma_f32_16x16x32_bf16 v[26:29], v[180:183], v[212:215], v[26:29]
	v_mfma_f32_16x16x32_bf16 v[22:25], v[188:191], v[212:215], v[22:25]
	v_mfma_f32_16x16x32_bf16 v[10:13], v[180:183], v[220:223], v[10:13]
	v_mfma_f32_16x16x32_bf16 v[4:7], v[188:191], v[220:223], v[4:7]
	s_barrier
	s_add_i32 s93, 0, 0x18000
	v_add_u32_e32 v3, s93, v176
	s_add_i32 s94, 0, 0x1c000
	ds_read_b128 v[134:137], v3
	ds_read_b128 v[138:141], v3 offset:1024
	ds_read_b128 v[142:145], v3 offset:2048
	ds_read_b128 v[146:149], v3 offset:3072
	v_add_u32_e32 v3, s94, v176
	ds_read_b128 v[150:153], v3
	ds_read_b128 v[180:183], v3 offset:1024
	ds_read_b128 v[184:187], v3 offset:2048
	ds_read_b128 v[188:191], v3 offset:3072
	s_add_u32 s66, s66, 0x80000
	s_addc_u32 s67, s67, 0
	s_mov_b32 m0, s74
	v_lshl_add_u64 v[8:9], s[66:67], 0, v[154:155]
	ds_read_b128 v[192:195], v178 offset:32768
	ds_read_b128 v[196:199], v178 offset:33792
	ds_read_b128 v[200:203], v178 offset:34816
	ds_read_b128 v[204:207], v178 offset:35840
	ds_read_b128 v[208:211], v178 offset:36864
	ds_read_b128 v[212:215], v178 offset:37888
	ds_read_b128 v[216:219], v178 offset:38912
	ds_read_b128 v[220:223], v178 offset:39936
	global_load_lds_dwordx4 v[8:9], off
	v_lshl_add_u64 v[8:9], s[66:67], 0, v[158:159]
	s_mov_b32 m0, s75
	s_nop 0
	global_load_lds_dwordx4 v[8:9], off
	s_waitcnt vmcnt(8)
	s_waitcnt lgkmcnt(0)
	s_barrier
	s_waitcnt lgkmcnt(0)
	v_mfma_f32_16x16x32_bf16 v[130:133], v[134:137], v[192:195], v[130:133]
	v_mfma_f32_16x16x32_bf16 v[126:129], v[142:145], v[192:195], v[126:129]
	v_mfma_f32_16x16x32_bf16 v[114:117], v[134:137], v[200:203], v[114:117]
	v_mfma_f32_16x16x32_bf16 v[110:113], v[142:145], v[200:203], v[110:113]
	v_mfma_f32_16x16x32_bf16 v[98:101], v[134:137], v[208:211], v[98:101]
	v_mfma_f32_16x16x32_bf16 v[94:97], v[142:145], v[208:211], v[94:97]
	v_mfma_f32_16x16x32_bf16 v[82:85], v[134:137], v[216:219], v[82:85]
	v_mfma_f32_16x16x32_bf16 v[78:81], v[142:145], v[216:219], v[78:81]
	v_mfma_f32_16x16x32_bf16 v[130:133], v[138:141], v[196:199], v[130:133]
	v_mfma_f32_16x16x32_bf16 v[126:129], v[146:149], v[196:199], v[126:129]
	v_mfma_f32_16x16x32_bf16 v[114:117], v[138:141], v[204:207], v[114:117]
	v_mfma_f32_16x16x32_bf16 v[110:113], v[146:149], v[204:207], v[110:113]
	v_mfma_f32_16x16x32_bf16 v[98:101], v[138:141], v[212:215], v[98:101]
	v_mfma_f32_16x16x32_bf16 v[94:97], v[146:149], v[212:215], v[94:97]
	v_mfma_f32_16x16x32_bf16 v[82:85], v[138:141], v[220:223], v[82:85]
	v_mfma_f32_16x16x32_bf16 v[78:81], v[146:149], v[220:223], v[78:81]
	v_mfma_f32_16x16x32_bf16 v[122:125], v[150:153], v[192:195], v[122:125]
	v_mfma_f32_16x16x32_bf16 v[118:121], v[184:187], v[192:195], v[118:121]
	v_mfma_f32_16x16x32_bf16 v[106:109], v[150:153], v[200:203], v[106:109]
	v_mfma_f32_16x16x32_bf16 v[102:105], v[184:187], v[200:203], v[102:105]
	v_mfma_f32_16x16x32_bf16 v[90:93], v[150:153], v[208:211], v[90:93]
	v_mfma_f32_16x16x32_bf16 v[86:89], v[184:187], v[208:211], v[86:89]
	v_mfma_f32_16x16x32_bf16 v[74:77], v[150:153], v[216:219], v[74:77]
	v_mfma_f32_16x16x32_bf16 v[70:73], v[184:187], v[216:219], v[70:73]
	v_mfma_f32_16x16x32_bf16 v[122:125], v[180:183], v[196:199], v[122:125]
	v_mfma_f32_16x16x32_bf16 v[118:121], v[188:191], v[196:199], v[118:121]
	v_mfma_f32_16x16x32_bf16 v[106:109], v[180:183], v[204:207], v[106:109]
	v_mfma_f32_16x16x32_bf16 v[102:105], v[188:191], v[204:207], v[102:105]
	v_mfma_f32_16x16x32_bf16 v[90:93], v[180:183], v[212:215], v[90:93]
	v_mfma_f32_16x16x32_bf16 v[86:89], v[188:191], v[212:215], v[86:89]
	v_mfma_f32_16x16x32_bf16 v[74:77], v[180:183], v[220:223], v[74:77]
	v_mfma_f32_16x16x32_bf16 v[70:73], v[188:191], v[220:223], v[70:73]
	s_barrier
; #define PG8_STAGE(bufoff, gbase, voff) do { _Pragma("unroll") for (int _i = 0; _i < 2; ++_i) \
;         __builtin_amdgcn_global_load_lds((const unsigned*)((const char*)(gbase) + (voff)[_i]), (PG8_LAS unsigned*)(lds + (bufoff) + ldsw + _i * 8192), 16, 0, 0); } while (0)
; #define PG8_LDA(dst, b, h) do { _Pragma("unroll") for (int m = 0; m < 4; ++m) _Pragma("unroll") for (int k = 0; k < 2; ++k) dst[m][k] = *(const PG8_LAS bf16x8*)(lds + PG8_SA(b, h) + aoff + m * 2048 + k * 1024); } while (0)
; #define PG8_MMA(ai, bj, At, Bt) do { __builtin_amdgcn_s_setprio(1); _Pragma("unroll") for (int m = 0; m < 4; ++m) _Pragma("unroll") for (int n = 0; n < 2; ++n) _Pragma("unroll") for (int k = 0; k < 2; ++k) \
;         acc[ai][bj][m][n] = __builtin_amdgcn_mfma_f32_16x16x32_bf16(Bt[n][k], At[m][k], acc[ai][bj][m][n], 0, 0, 0); __builtin_amdgcn_s_setprio(0); } while (0)
; #define PG8_WAIT_V(n) asm volatile("s_waitcnt vmcnt(" #n ")" ::: "memory")
; #define PG8_WAIT_L(n) asm volatile("s_waitcnt lgkmcnt(" #n ")" ::: "memory")
; #define PG8_BAR __builtin_amdgcn_s_barrier()
; #define PG8_SCHED __builtin_amdgcn_sched_barrier(0)
; template <class Epi, class Sched, bool ALIGN_EPI = false, bool SP2 = false>
; __device__ __forceinline__ void gemm_phase(PG8_LAS unsigned char* lds, const Gemm g, const Sched& S, const Epi& E) {
;     ...
;         for (int t = 0; t < nt; t += 2) {
;     ...
;             PG8_LDA(At, 1, 1); PG8_STAGE(PG8_SB(1, 0), b3, voffB); PG8_STAGE(PG8_SB(1, 1), b3 + hstep, voffB); PG8_STAGE(PG8_SA(1, 0), a3, voffA);
;             PG8_WAIT_V(8); PG8_WAIT_L(0); PG8_BAR; PG8_MMA(1, 0, At, B0); PG8_MMA(1, 1, At, B1); PG8_BAR; PG8_SCHED;
	s_add_i32 s66, s93, s71
	v_lshl_add_u64 v[8:9], v[224:225], 0, s[10:11]
	s_mov_b32 m0, s66
	ds_read_b128 v[192:195], v178 offset:49152
	ds_read_b128 v[196:199], v178 offset:50176
	ds_read_b128 v[200:203], v178 offset:51200
	ds_read_b128 v[204:207], v178 offset:52224
	ds_read_b128 v[208:211], v178 offset:53248
	ds_read_b128 v[212:215], v178 offset:54272
	ds_read_b128 v[216:219], v178 offset:55296
	ds_read_b128 v[220:223], v178 offset:56320
	global_load_lds_dwordx4 v[8:9], off
	s_add_i32 m0, s66, 0x2000
	s_add_u32 s64, s64, 0x80080
	v_lshl_add_u64 v[8:9], v[226:227], 0, s[10:11]
	s_addc_u32 s65, s65, 0
	s_add_i32 s66, s94, s71
	global_load_lds_dwordx4 v[8:9], off
	v_lshl_add_u64 v[8:9], s[64:65], 0, v[156:157]
	s_mov_b32 m0, s66
	s_nop 0
	global_load_lds_dwordx4 v[8:9], off
	v_lshl_add_u64 v[8:9], s[64:65], 0, v[160:161]
	s_add_i32 m0, s66, 0x2000
	s_nop 0
	global_load_lds_dwordx4 v[8:9], off
	v_lshl_add_u64 v[8:9], v[228:229], 0, s[10:11]
	s_mov_b32 m0, s79
	s_nop 0
	global_load_lds_dwordx4 v[8:9], off
	v_lshl_add_u64 v[8:9], v[230:231], 0, s[10:11]
	s_mov_b32 m0, s80
	s_nop 0
	global_load_lds_dwordx4 v[8:9], off
	s_waitcnt vmcnt(8)
	s_waitcnt lgkmcnt(0)
	s_barrier
	s_waitcnt lgkmcnt(0)
	v_mfma_f32_16x16x32_bf16 v[66:69], v[134:137], v[192:195], v[66:69]
	v_mfma_f32_16x16x32_bf16 v[62:65], v[142:145], v[192:195], v[62:65]
	v_mfma_f32_16x16x32_bf16 v[50:53], v[134:137], v[200:203], v[50:53]
	v_mfma_f32_16x16x32_bf16 v[46:49], v[142:145], v[200:203], v[46:49]
	v_mfma_f32_16x16x32_bf16 v[34:37], v[134:137], v[208:211], v[34:37]
	v_mfma_f32_16x16x32_bf16 v[30:33], v[142:145], v[208:211], v[30:33]
	v_mfma_f32_16x16x32_bf16 v[18:21], v[134:137], v[216:219], v[18:21]
	v_mfma_f32_16x16x32_bf16 v[14:17], v[142:145], v[216:219], v[14:17]
	v_mfma_f32_16x16x32_bf16 v[66:69], v[138:141], v[196:199], v[66:69]
	v_mfma_f32_16x16x32_bf16 v[62:65], v[146:149], v[196:199], v[62:65]
	v_mfma_f32_16x16x32_bf16 v[50:53], v[138:141], v[204:207], v[50:53]
	v_mfma_f32_16x16x32_bf16 v[46:49], v[146:149], v[204:207], v[46:49]
	v_mfma_f32_16x16x32_bf16 v[34:37], v[138:141], v[212:215], v[34:37]
	v_mfma_f32_16x16x32_bf16 v[30:33], v[146:149], v[212:215], v[30:33]
	v_mfma_f32_16x16x32_bf16 v[18:21], v[138:141], v[220:223], v[18:21]
	v_mfma_f32_16x16x32_bf16 v[14:17], v[146:149], v[220:223], v[14:17]
	v_mfma_f32_16x16x32_bf16 v[58:61], v[150:153], v[192:195], v[58:61]
	v_mfma_f32_16x16x32_bf16 v[54:57], v[184:187], v[192:195], v[54:57]
	v_mfma_f32_16x16x32_bf16 v[42:45], v[150:153], v[200:203], v[42:45]
	v_mfma_f32_16x16x32_bf16 v[38:41], v[184:187], v[200:203], v[38:41]
	v_mfma_f32_16x16x32_bf16 v[26:29], v[150:153], v[208:211], v[26:29]
	v_mfma_f32_16x16x32_bf16 v[22:25], v[184:187], v[208:211], v[22:25]
	v_mfma_f32_16x16x32_bf16 v[8:11], v[150:153], v[216:219], v[10:13]
	v_mfma_f32_16x16x32_bf16 v[4:7], v[184:187], v[216:219], v[4:7]
	v_mfma_f32_16x16x32_bf16 v[58:61], v[180:183], v[196:199], v[58:61]
	v_mfma_f32_16x16x32_bf16 v[54:57], v[188:191], v[196:199], v[54:57]
	v_mfma_f32_16x16x32_bf16 v[42:45], v[180:183], v[204:207], v[42:45]
	v_mfma_f32_16x16x32_bf16 v[38:41], v[188:191], v[204:207], v[38:41]
	v_mfma_f32_16x16x32_bf16 v[26:29], v[180:183], v[212:215], v[26:29]
	v_mfma_f32_16x16x32_bf16 v[22:25], v[188:191], v[212:215], v[22:25]
	v_mfma_f32_16x16x32_bf16 v[10:13], v[180:183], v[220:223], v[8:11]
	v_mfma_f32_16x16x32_bf16 v[6:9], v[188:191], v[220:223], v[4:7]
	s_add_i32 s92, s92, 2
	s_add_u32 s62, s62, 0x100
	s_addc_u32 s63, s63, 0
	s_cmp_gt_u32 s92, 29
	s_barrier
	s_cbranch_scc1 .LBB0_478

; #define PG8_STAGE(bufoff, gbase, voff) do { _Pragma("unroll") for (int _i = 0; _i < 2; ++_i) \
;         __builtin_amdgcn_global_load_lds((const unsigned*)((const char*)(gbase) + (voff)[_i]), (PG8_LAS unsigned*)(lds + (bufoff) + ldsw + _i * 8192), 16, 0, 0); } while (0)
; #define PG8_LDA(dst, b, h) do { _Pragma("unroll") for (int m = 0; m < 4; ++m) _Pragma("unroll") for (int k = 0; k < 2; ++k) dst[m][k] = *(const PG8_LAS bf16x8*)(lds + PG8_SA(b, h) + aoff + m * 2048 + k * 1024); } while (0)
; #define PG8_LDB(dst, b, h) do { _Pragma("unroll") for (int n = 0; n < 2; ++n) _Pragma("unroll") for (int k = 0; k < 2; ++k) dst[n][k] = *(const PG8_LAS bf16x8*)(lds + PG8_SB(b, h) + boff + n * 2048 + k * 1024); } while (0)
; #define PG8_MMA(ai, bj, At, Bt) do { __builtin_amdgcn_s_setprio(1); _Pragma("unroll") for (int m = 0; m < 4; ++m) _Pragma("unroll") for (int n = 0; n < 2; ++n) _Pragma("unroll") for (int k = 0; k < 2; ++k) \
;         acc[ai][bj][m][n] = __builtin_amdgcn_mfma_f32_16x16x32_bf16(Bt[n][k], At[m][k], acc[ai][bj][m][n], 0, 0, 0); __builtin_amdgcn_s_setprio(0); } while (0)
; #define PG8_WAIT_V(n) asm volatile("s_waitcnt vmcnt(" #n ")" ::: "memory")
; #define PG8_WAIT_L(n) asm volatile("s_waitcnt lgkmcnt(" #n ")" ::: "memory")
; #define PG8_BAR __builtin_amdgcn_s_barrier()
; #define PG8_SCHED __builtin_amdgcn_sched_barrier(0)
; template <class Epi, class Sched, bool ALIGN_EPI = false, bool SP2 = false>
; __device__ __forceinline__ void gemm_phase(PG8_LAS unsigned char* lds, const Gemm g, const Sched& S, const Epi& E) {
;     ...
;             const bool last = (t == nt - 2);
;             const char* a1 = cA + (size_t)(t + 1) * kstep;
;             const char* a2 = last ? nA : cA + (size_t)(t + 2) * kstep; const char* b2 = last ? nB : cB + (size_t)(t + 2) * kstep;
;             const char* a3 = a2 + kstep; const char* b3 = b2 + kstep;
;             if (last && has_next) S.a_ready(nxt);
;             if constexpr (SP2) {
;             PG8_LDB(B0, 0, 0); PG8_LDB(B1, 0, 1); PG8_SCHED; PG8_LDA(At, 0, 0); PG8_STAGE(PG8_SA(1, 1), a1 + hstep, voffA);
;             PG8_WAIT_V(8); PG8_WAIT_L(0); PG8_BAR; PG8_MMA(0, 0, At, B0); PG8_MMA(0, 1, At, B1); PG8_BAR; PG8_SCHED;
;             PG8_LDA(At, 0, 1); PG8_STAGE(PG8_SB(0, 0), b2, voffB); PG8_STAGE(PG8_SB(0, 1), b2 + hstep, voffB); PG8_STAGE(PG8_SA(0, 0), a2, voffA);
.LBB0_558:
	ds_read_b128 v[140:143], v181
	ds_read_b128 v[144:147], v181 offset:1024
	ds_read_b128 v[148:151], v181 offset:2048
	ds_read_b128 v[152:155], v181 offset:3072
	ds_read_b128 v[156:159], v182
	ds_read_b128 v[160:163], v182 offset:1024
	ds_read_b128 v[164:167], v182 offset:2048
	ds_read_b128 v[168:171], v182 offset:3072
	s_add_u32 s48, s46, 0xfffc0080
	s_addc_u32 s49, s47, -1
	s_cmp_eq_u32 s70, 12
	s_cselect_b32 s51, s9, s49
	s_cselect_b32 s50, s39, s48
	s_cselect_b32 s49, s31, s69
	s_cselect_b32 s48, s45, s68
	v_lshl_add_u64 v[176:177], s[46:47], 0, v[132:133]
	s_add_i32 m0, s54, 0xc000
	ds_read_b128 v[172:175], v183
	ds_read_b128 v[188:191], v183 offset:1024
	ds_read_b128 v[192:195], v183 offset:2048
	ds_read_b128 v[196:199], v183 offset:3072
	ds_read_b128 v[200:203], v183 offset:4096
	ds_read_b128 v[204:207], v183 offset:5120
	ds_read_b128 v[208:211], v183 offset:6144
	ds_read_b128 v[212:215], v183 offset:7168
	global_load_lds_dwordx4 v[176:177], off
	v_lshl_add_u64 v[176:177], s[46:47], 0, v[134:135]
	s_add_i32 m0, s54, 0xe000
	s_nop 0
	global_load_lds_dwordx4 v[176:177], off
	s_waitcnt vmcnt(8)
	s_waitcnt lgkmcnt(0)
	s_barrier
	s_waitcnt lgkmcnt(0)
	v_mfma_f32_16x16x32_bf16 v[124:127], v[140:143], v[172:175], v[124:127]
	v_mfma_f32_16x16x32_bf16 v[120:123], v[148:151], v[172:175], v[120:123]
	v_mfma_f32_16x16x32_bf16 v[108:111], v[140:143], v[192:195], v[108:111]
	v_mfma_f32_16x16x32_bf16 v[104:107], v[148:151], v[192:195], v[104:107]
	v_mfma_f32_16x16x32_bf16 v[92:95], v[140:143], v[200:203], v[92:95]
	v_mfma_f32_16x16x32_bf16 v[88:91], v[148:151], v[200:203], v[88:91]
	v_mfma_f32_16x16x32_bf16 v[76:79], v[140:143], v[208:211], v[76:79]
	v_mfma_f32_16x16x32_bf16 v[72:75], v[148:151], v[208:211], v[72:75]
	v_mfma_f32_16x16x32_bf16 v[124:127], v[144:147], v[188:191], v[124:127]
	v_mfma_f32_16x16x32_bf16 v[120:123], v[152:155], v[188:191], v[120:123]
	v_mfma_f32_16x16x32_bf16 v[108:111], v[144:147], v[196:199], v[108:111]
	v_mfma_f32_16x16x32_bf16 v[104:107], v[152:155], v[196:199], v[104:107]
	v_mfma_f32_16x16x32_bf16 v[92:95], v[144:147], v[204:207], v[92:95]
	v_mfma_f32_16x16x32_bf16 v[88:91], v[152:155], v[204:207], v[88:91]
	v_mfma_f32_16x16x32_bf16 v[76:79], v[144:147], v[212:215], v[76:79]
	v_mfma_f32_16x16x32_bf16 v[72:75], v[152:155], v[212:215], v[72:75]
	v_mfma_f32_16x16x32_bf16 v[116:119], v[156:159], v[172:175], v[116:119]
	v_mfma_f32_16x16x32_bf16 v[112:115], v[164:167], v[172:175], v[112:115]
	v_mfma_f32_16x16x32_bf16 v[100:103], v[156:159], v[192:195], v[100:103]
	v_mfma_f32_16x16x32_bf16 v[96:99], v[164:167], v[192:195], v[96:99]
	v_mfma_f32_16x16x32_bf16 v[84:87], v[156:159], v[200:203], v[84:87]
	v_mfma_f32_16x16x32_bf16 v[80:83], v[164:167], v[200:203], v[80:83]
	v_mfma_f32_16x16x32_bf16 v[68:71], v[156:159], v[208:211], v[68:71]
	v_mfma_f32_16x16x32_bf16 v[64:67], v[164:167], v[208:211], v[64:67]
	v_mfma_f32_16x16x32_bf16 v[116:119], v[160:163], v[188:191], v[116:119]
	v_mfma_f32_16x16x32_bf16 v[112:115], v[168:171], v[188:191], v[112:115]
	v_mfma_f32_16x16x32_bf16 v[100:103], v[160:163], v[196:199], v[100:103]
	v_mfma_f32_16x16x32_bf16 v[96:99], v[168:171], v[196:199], v[96:99]
	v_mfma_f32_16x16x32_bf16 v[84:87], v[160:163], v[204:207], v[84:87]
	v_mfma_f32_16x16x32_bf16 v[80:83], v[168:171], v[204:207], v[80:83]
	v_mfma_f32_16x16x32_bf16 v[68:71], v[160:163], v[212:215], v[68:71]
	v_mfma_f32_16x16x32_bf16 v[64:67], v[168:171], v[212:215], v[64:67]
	s_barrier
	s_add_i32 s71, s65, s53
	v_lshl_add_u64 v[176:177], s[48:49], 0, v[128:129]
	s_mov_b32 m0, s71
	ds_read_b128 v[172:175], v183 offset:16384
	ds_read_b128 v[188:191], v183 offset:17408
	ds_read_b128 v[192:195], v183 offset:18432
	ds_read_b128 v[196:199], v183 offset:19456
	ds_read_b128 v[200:203], v183 offset:20480
	ds_read_b128 v[204:207], v183 offset:21504
	ds_read_b128 v[208:211], v183 offset:22528
	ds_read_b128 v[212:215], v183 offset:23552
	global_load_lds_dwordx4 v[176:177], off
	s_add_i32 m0, s71, 0x2000
	s_add_u32 s72, s48, 0x40000
	v_lshl_add_u64 v[216:217], s[48:49], 0, v[130:131]
	s_addc_u32 s73, s49, 0
	s_add_i32 s71, s66, s53
	global_load_lds_dwordx4 v[216:217], off
	v_lshl_add_u64 v[218:219], s[72:73], 0, v[128:129]
	s_mov_b32 m0, s71
	v_lshl_add_u64 v[220:221], s[50:51], 0, v[130:131]
	global_load_lds_dwordx4 v[218:219], off
	v_lshl_add_u64 v[218:219], s[72:73], 0, v[130:131]
	s_add_i32 m0, s71, 0x2000
	s_nop 0
	global_load_lds_dwordx4 v[218:219], off
	v_lshl_add_u64 v[218:219], s[50:51], 0, v[128:129]
	s_mov_b32 m0, s54
	s_nop 0
	global_load_lds_dwordx4 v[218:219], off
	s_mov_b32 m0, s55
	s_nop 0
	global_load_lds_dwordx4 v[220:221], off
	s_waitcnt vmcnt(8)
	s_waitcnt lgkmcnt(0)
	s_barrier
; #define PG8_STAGE(bufoff, gbase, voff) do { _Pragma("unroll") for (int _i = 0; _i < 2; ++_i) \
;         __builtin_amdgcn_global_load_lds((const unsigned*)((const char*)(gbase) + (voff)[_i]), (PG8_LAS unsigned*)(lds + (bufoff) + ldsw + _i * 8192), 16, 0, 0); } while (0)
; #define PG8_LDA(dst, b, h) do { _Pragma("unroll") for (int m = 0; m < 4; ++m) _Pragma("unroll") for (int k = 0; k < 2; ++k) dst[m][k] = *(const PG8_LAS bf16x8*)(lds + PG8_SA(b, h) + aoff + m * 2048 + k * 1024); } while (0)
; #define PG8_LDB(dst, b, h) do { _Pragma("unroll") for (int n = 0; n < 2; ++n) _Pragma("unroll") for (int k = 0; k < 2; ++k) dst[n][k] = *(const PG8_LAS bf16x8*)(lds + PG8_SB(b, h) + boff + n * 2048 + k * 1024); } while (0)
; #define PG8_MMA(ai, bj, At, Bt) do { __builtin_amdgcn_s_setprio(1); _Pragma("unroll") for (int m = 0; m < 4; ++m) _Pragma("unroll") for (int n = 0; n < 2; ++n) _Pragma("unroll") for (int k = 0; k < 2; ++k) \
;         acc[ai][bj][m][n] = __builtin_amdgcn_mfma_f32_16x16x32_bf16(Bt[n][k], At[m][k], acc[ai][bj][m][n], 0, 0, 0); __builtin_amdgcn_s_setprio(0); } while (0)
; #define PG8_WAIT_V(n) asm volatile("s_waitcnt vmcnt(" #n ")" ::: "memory")
; #define PG8_WAIT_L(n) asm volatile("s_waitcnt lgkmcnt(" #n ")" ::: "memory")
; #define PG8_BAR __builtin_amdgcn_s_barrier()
; #define PG8_SCHED __builtin_amdgcn_sched_barrier(0)
; template <class Epi, class Sched, bool ALIGN_EPI = false, bool SP2 = false>
; __device__ __forceinline__ void gemm_phase(PG8_LAS unsigned char* lds, const Gemm g, const Sched& S, const Epi& E) {
;     ...
;             PG8_WAIT_V(8); PG8_WAIT_L(0); PG8_BAR; PG8_MMA(1, 0, At, B0); PG8_MMA(1, 1, At, B1); PG8_BAR; PG8_SCHED;
;             PG8_LDB(B0, 1, 0); PG8_LDB(B1, 1, 1); PG8_SCHED; PG8_LDA(At, 1, 0); PG8_STAGE(PG8_SA(0, 1), a2 + hstep, voffA);
;             PG8_WAIT_V(8); PG8_WAIT_L(0); PG8_BAR; PG8_MMA(0, 0, At, B0); PG8_MMA(0, 1, At, B1); PG8_BAR; PG8_SCHED;
	s_waitcnt lgkmcnt(0)
	v_mfma_f32_16x16x32_bf16 v[60:63], v[140:143], v[172:175], v[60:63]
	v_mfma_f32_16x16x32_bf16 v[56:59], v[148:151], v[172:175], v[56:59]
	v_mfma_f32_16x16x32_bf16 v[44:47], v[140:143], v[192:195], v[44:47]
	v_mfma_f32_16x16x32_bf16 v[40:43], v[148:151], v[192:195], v[40:43]
	v_mfma_f32_16x16x32_bf16 v[28:31], v[140:143], v[200:203], v[28:31]
	v_mfma_f32_16x16x32_bf16 v[24:27], v[148:151], v[200:203], v[24:27]
	v_mfma_f32_16x16x32_bf16 v[12:15], v[140:143], v[208:211], v[12:15]
	v_mfma_f32_16x16x32_bf16 v[8:11], v[148:151], v[208:211], v[8:11]
	v_mfma_f32_16x16x32_bf16 v[60:63], v[144:147], v[188:191], v[60:63]
	v_mfma_f32_16x16x32_bf16 v[56:59], v[152:155], v[188:191], v[56:59]
	v_mfma_f32_16x16x32_bf16 v[44:47], v[144:147], v[196:199], v[44:47]
	v_mfma_f32_16x16x32_bf16 v[40:43], v[152:155], v[196:199], v[40:43]
	v_mfma_f32_16x16x32_bf16 v[28:31], v[144:147], v[204:207], v[28:31]
	v_mfma_f32_16x16x32_bf16 v[24:27], v[152:155], v[204:207], v[24:27]
	v_mfma_f32_16x16x32_bf16 v[12:15], v[144:147], v[212:215], v[12:15]
	v_mfma_f32_16x16x32_bf16 v[8:11], v[152:155], v[212:215], v[8:11]
	v_mfma_f32_16x16x32_bf16 v[52:55], v[156:159], v[172:175], v[52:55]
	v_mfma_f32_16x16x32_bf16 v[48:51], v[164:167], v[172:175], v[48:51]
	v_mfma_f32_16x16x32_bf16 v[36:39], v[156:159], v[192:195], v[36:39]
	v_mfma_f32_16x16x32_bf16 v[32:35], v[164:167], v[192:195], v[32:35]
	v_mfma_f32_16x16x32_bf16 v[20:23], v[156:159], v[200:203], v[20:23]
	v_mfma_f32_16x16x32_bf16 v[16:19], v[164:167], v[200:203], v[16:19]
	v_mfma_f32_16x16x32_bf16 v[4:7], v[156:159], v[208:211], v[4:7]
	v_mfma_f32_16x16x32_bf16 v[0:3], v[164:167], v[208:211], v[0:3]
	v_mfma_f32_16x16x32_bf16 v[52:55], v[160:163], v[188:191], v[52:55]
	v_mfma_f32_16x16x32_bf16 v[48:51], v[168:171], v[188:191], v[48:51]
	v_mfma_f32_16x16x32_bf16 v[36:39], v[160:163], v[196:199], v[36:39]
	v_mfma_f32_16x16x32_bf16 v[32:35], v[168:171], v[196:199], v[32:35]
	v_mfma_f32_16x16x32_bf16 v[20:23], v[160:163], v[204:207], v[20:23]
	v_mfma_f32_16x16x32_bf16 v[16:19], v[168:171], v[204:207], v[16:19]
	v_mfma_f32_16x16x32_bf16 v[4:7], v[160:163], v[212:215], v[4:7]
	v_mfma_f32_16x16x32_bf16 v[0:3], v[168:171], v[212:215], v[0:3]
	s_barrier
	s_add_i32 s71, 0, 0x18000
	s_add_i32 s72, 0, 0x1c000
	v_add_u32_e32 v152, s71, v179
	v_add_u32_e32 v168, s72, v179
	ds_read_b128 v[140:143], v152
	ds_read_b128 v[144:147], v152 offset:1024
	ds_read_b128 v[148:151], v152 offset:2048
	ds_read_b128 v[152:155], v152 offset:3072
	ds_read_b128 v[156:159], v168
	ds_read_b128 v[160:163], v168 offset:1024
	ds_read_b128 v[164:167], v168 offset:2048
	ds_read_b128 v[168:171], v168 offset:3072
	s_add_u32 s50, s50, 0x40000
	s_addc_u32 s51, s51, 0
	s_mov_b32 m0, s56
	v_lshl_add_u64 v[222:223], s[50:51], 0, v[128:129]
	ds_read_b128 v[172:175], v183 offset:32768
	ds_read_b128 v[188:191], v183 offset:33792
	ds_read_b128 v[192:195], v183 offset:34816
	ds_read_b128 v[196:199], v183 offset:35840
	ds_read_b128 v[200:203], v183 offset:36864
	ds_read_b128 v[204:207], v183 offset:37888
	ds_read_b128 v[208:211], v183 offset:38912
	ds_read_b128 v[212:215], v183 offset:39936
	global_load_lds_dwordx4 v[222:223], off
	v_lshl_add_u64 v[222:223], s[50:51], 0, v[130:131]
	s_mov_b32 m0, s57
	s_nop 0
	global_load_lds_dwordx4 v[222:223], off
	s_waitcnt vmcnt(8)
	s_waitcnt lgkmcnt(0)
	s_barrier
	s_waitcnt lgkmcnt(0)
	v_mfma_f32_16x16x32_bf16 v[124:127], v[140:143], v[172:175], v[124:127]
	v_mfma_f32_16x16x32_bf16 v[120:123], v[148:151], v[172:175], v[120:123]
	v_mfma_f32_16x16x32_bf16 v[108:111], v[140:143], v[192:195], v[108:111]
	v_mfma_f32_16x16x32_bf16 v[104:107], v[148:151], v[192:195], v[104:107]
	v_mfma_f32_16x16x32_bf16 v[92:95], v[140:143], v[200:203], v[92:95]
	v_mfma_f32_16x16x32_bf16 v[88:91], v[148:151], v[200:203], v[88:91]
	v_mfma_f32_16x16x32_bf16 v[76:79], v[140:143], v[208:211], v[76:79]
	v_mfma_f32_16x16x32_bf16 v[72:75], v[148:151], v[208:211], v[72:75]
	v_mfma_f32_16x16x32_bf16 v[124:127], v[144:147], v[188:191], v[124:127]
	v_mfma_f32_16x16x32_bf16 v[120:123], v[152:155], v[188:191], v[120:123]
	v_mfma_f32_16x16x32_bf16 v[108:111], v[144:147], v[196:199], v[108:111]
	v_mfma_f32_16x16x32_bf16 v[104:107], v[152:155], v[196:199], v[104:107]
	v_mfma_f32_16x16x32_bf16 v[92:95], v[144:147], v[204:207], v[92:95]
	v_mfma_f32_16x16x32_bf16 v[88:91], v[152:155], v[204:207], v[88:91]
	v_mfma_f32_16x16x32_bf16 v[76:79], v[144:147], v[212:215], v[76:79]
	v_mfma_f32_16x16x32_bf16 v[72:75], v[152:155], v[212:215], v[72:75]
	v_mfma_f32_16x16x32_bf16 v[116:119], v[156:159], v[172:175], v[116:119]
	v_mfma_f32_16x16x32_bf16 v[112:115], v[164:167], v[172:175], v[112:115]
	v_mfma_f32_16x16x32_bf16 v[100:103], v[156:159], v[192:195], v[100:103]
	v_mfma_f32_16x16x32_bf16 v[96:99], v[164:167], v[192:195], v[96:99]
	v_mfma_f32_16x16x32_bf16 v[84:87], v[156:159], v[200:203], v[84:87]
	v_mfma_f32_16x16x32_bf16 v[80:83], v[164:167], v[200:203], v[80:83]
	v_mfma_f32_16x16x32_bf16 v[68:71], v[156:159], v[208:211], v[68:71]
	v_mfma_f32_16x16x32_bf16 v[64:67], v[164:167], v[208:211], v[64:67]
	v_mfma_f32_16x16x32_bf16 v[116:119], v[160:163], v[188:191], v[116:119]
	v_mfma_f32_16x16x32_bf16 v[112:115], v[168:171], v[188:191], v[112:115]
	v_mfma_f32_16x16x32_bf16 v[100:103], v[160:163], v[196:199], v[100:103]
	v_mfma_f32_16x16x32_bf16 v[96:99], v[168:171], v[196:199], v[96:99]
	v_mfma_f32_16x16x32_bf16 v[84:87], v[160:163], v[204:207], v[84:87]
	v_mfma_f32_16x16x32_bf16 v[80:83], v[168:171], v[204:207], v[80:83]
	v_mfma_f32_16x16x32_bf16 v[68:71], v[160:163], v[212:215], v[68:71]
	v_mfma_f32_16x16x32_bf16 v[64:67], v[168:171], v[212:215], v[64:67]
	s_barrier
; #define PG8_STAGE(bufoff, gbase, voff) do { _Pragma("unroll") for (int _i = 0; _i < 2; ++_i) \
;         __builtin_amdgcn_global_load_lds((const unsigned*)((const char*)(gbase) + (voff)[_i]), (PG8_LAS unsigned*)(lds + (bufoff) + ldsw + _i * 8192), 16, 0, 0); } while (0)
; #define PG8_LDA(dst, b, h) do { _Pragma("unroll") for (int m = 0; m < 4; ++m) _Pragma("unroll") for (int k = 0; k < 2; ++k) dst[m][k] = *(const PG8_LAS bf16x8*)(lds + PG8_SA(b, h) + aoff + m * 2048 + k * 1024); } while (0)
; #define PG8_MMA(ai, bj, At, Bt) do { __builtin_amdgcn_s_setprio(1); _Pragma("unroll") for (int m = 0; m < 4; ++m) _Pragma("unroll") for (int n = 0; n < 2; ++n) _Pragma("unroll") for (int k = 0; k < 2; ++k) \
;         acc[ai][bj][m][n] = __builtin_amdgcn_mfma_f32_16x16x32_bf16(Bt[n][k], At[m][k], acc[ai][bj][m][n], 0, 0, 0); __builtin_amdgcn_s_setprio(0); } while (0)
; #define PG8_WAIT_V(n) asm volatile("s_waitcnt vmcnt(" #n ")" ::: "memory")
; #define PG8_WAIT_L(n) asm volatile("s_waitcnt lgkmcnt(" #n ")" ::: "memory")
; #define PG8_BAR __builtin_amdgcn_s_barrier()
; #define PG8_SCHED __builtin_amdgcn_sched_barrier(0)
; template <class Epi, class Sched, bool ALIGN_EPI = false, bool SP2 = false>
; __device__ __forceinline__ void gemm_phase(PG8_LAS unsigned char* lds, const Gemm g, const Sched& S, const Epi& E) {
;     ...
;         for (int t = 0; t < nt; t += 2) {
;     ...
;             PG8_LDA(At, 1, 1); PG8_STAGE(PG8_SB(1, 0), b3, voffB); PG8_STAGE(PG8_SB(1, 1), b3 + hstep, voffB); PG8_STAGE(PG8_SA(1, 0), a3, voffA);
;             PG8_WAIT_V(8); PG8_WAIT_L(0); PG8_BAR; PG8_MMA(1, 0, At, B0); PG8_MMA(1, 1, At, B1); PG8_BAR; PG8_SCHED;
;     ...
;         if constexpr (ALIGN_EPI) { if (wr == 0) PG8_BAR; }
	s_add_i32 s50, s71, s53
	v_lshl_add_u64 v[176:177], v[176:177], 0, s[12:13]
	s_mov_b32 m0, s50
	ds_read_b128 v[172:175], v183 offset:49152
	ds_read_b128 v[188:191], v183 offset:50176
	ds_read_b128 v[192:195], v183 offset:51200
	ds_read_b128 v[196:199], v183 offset:52224
	ds_read_b128 v[200:203], v183 offset:53248
	ds_read_b128 v[204:207], v183 offset:54272
	ds_read_b128 v[208:211], v183 offset:55296
	ds_read_b128 v[212:215], v183 offset:56320
	global_load_lds_dwordx4 v[176:177], off
	s_add_i32 m0, s50, 0x2000
	s_add_u32 s48, s48, 0x40080
	v_lshl_add_u64 v[176:177], v[216:217], 0, s[12:13]
	s_addc_u32 s49, s49, 0
	s_add_i32 s50, s72, s53
	global_load_lds_dwordx4 v[176:177], off
	v_lshl_add_u64 v[176:177], s[48:49], 0, v[128:129]
	s_mov_b32 m0, s50
	s_nop 0
	global_load_lds_dwordx4 v[176:177], off
	v_lshl_add_u64 v[176:177], s[48:49], 0, v[130:131]
	s_add_i32 m0, s50, 0x2000
	s_nop 0
	global_load_lds_dwordx4 v[176:177], off
	v_lshl_add_u64 v[176:177], v[218:219], 0, s[12:13]
	s_mov_b32 m0, s61
	s_nop 0
	global_load_lds_dwordx4 v[176:177], off
	v_lshl_add_u64 v[176:177], v[220:221], 0, s[12:13]
	s_mov_b32 m0, s62
	s_nop 0
	global_load_lds_dwordx4 v[176:177], off
	s_waitcnt vmcnt(8)
	s_waitcnt lgkmcnt(0)
	s_barrier
	s_waitcnt lgkmcnt(0)
	v_mfma_f32_16x16x32_bf16 v[60:63], v[140:143], v[172:175], v[60:63]
	v_mfma_f32_16x16x32_bf16 v[56:59], v[148:151], v[172:175], v[56:59]
	v_mfma_f32_16x16x32_bf16 v[44:47], v[140:143], v[192:195], v[44:47]
	v_mfma_f32_16x16x32_bf16 v[40:43], v[148:151], v[192:195], v[40:43]
	v_mfma_f32_16x16x32_bf16 v[28:31], v[140:143], v[200:203], v[28:31]
	v_mfma_f32_16x16x32_bf16 v[24:27], v[148:151], v[200:203], v[24:27]
	v_mfma_f32_16x16x32_bf16 v[12:15], v[140:143], v[208:211], v[12:15]
	v_mfma_f32_16x16x32_bf16 v[8:11], v[148:151], v[208:211], v[8:11]
	v_mfma_f32_16x16x32_bf16 v[60:63], v[144:147], v[188:191], v[60:63]
	v_mfma_f32_16x16x32_bf16 v[56:59], v[152:155], v[188:191], v[56:59]
	v_mfma_f32_16x16x32_bf16 v[44:47], v[144:147], v[196:199], v[44:47]
	v_mfma_f32_16x16x32_bf16 v[40:43], v[152:155], v[196:199], v[40:43]
	v_mfma_f32_16x16x32_bf16 v[28:31], v[144:147], v[204:207], v[28:31]
	v_mfma_f32_16x16x32_bf16 v[24:27], v[152:155], v[204:207], v[24:27]
	v_mfma_f32_16x16x32_bf16 v[12:15], v[144:147], v[212:215], v[12:15]
	v_mfma_f32_16x16x32_bf16 v[8:11], v[152:155], v[212:215], v[8:11]
	v_mfma_f32_16x16x32_bf16 v[52:55], v[156:159], v[172:175], v[52:55]
	v_mfma_f32_16x16x32_bf16 v[48:51], v[164:167], v[172:175], v[48:51]
	v_mfma_f32_16x16x32_bf16 v[36:39], v[156:159], v[192:195], v[36:39]
	v_mfma_f32_16x16x32_bf16 v[32:35], v[164:167], v[192:195], v[32:35]
	v_mfma_f32_16x16x32_bf16 v[20:23], v[156:159], v[200:203], v[20:23]
	v_mfma_f32_16x16x32_bf16 v[16:19], v[164:167], v[200:203], v[16:19]
	v_mfma_f32_16x16x32_bf16 v[4:7], v[156:159], v[208:211], v[4:7]
	v_mfma_f32_16x16x32_bf16 v[0:3], v[164:167], v[208:211], v[0:3]
	v_mfma_f32_16x16x32_bf16 v[52:55], v[160:163], v[188:191], v[52:55]
	v_mfma_f32_16x16x32_bf16 v[48:51], v[168:171], v[188:191], v[48:51]
	v_mfma_f32_16x16x32_bf16 v[36:39], v[160:163], v[196:199], v[36:39]
	v_mfma_f32_16x16x32_bf16 v[32:35], v[168:171], v[196:199], v[32:35]
	v_mfma_f32_16x16x32_bf16 v[20:23], v[160:163], v[204:207], v[20:23]
	v_mfma_f32_16x16x32_bf16 v[16:19], v[168:171], v[204:207], v[16:19]
	v_mfma_f32_16x16x32_bf16 v[4:7], v[160:163], v[212:215], v[4:7]
	v_mfma_f32_16x16x32_bf16 v[0:3], v[168:171], v[212:215], v[0:3]
	s_add_i32 s70, s70, 2
	s_add_u32 s46, s46, 0x100
	s_addc_u32 s47, s47, 0
	s_add_u32 s68, s68, 0x100
	s_addc_u32 s69, s69, 0
	s_cmp_gt_u32 s70, 13
	s_barrier
	s_cbranch_scc0 .LBB0_558
	s_and_b64 vcc, exec, s[14:15]
	s_cbranch_vccz .LBB0_561
	s_barrier
